# v36 with lever 4: one static s_setprio 1 for waves 4..7 at kernel entry, all 80 per-segment s_setprio flips of the GEMM mainloops deleted
# baseline (speedup 1.0000x reference)
_Z10fwd_kernel4Args:
	s_load_dwordx16 s[56:71], s[0:1], 0x0
	s_load_dwordx16 s[4:19], s[0:1], 0x40
	s_load_dwordx16 s[40:55], s[0:1], 0xc0
	s_load_dword s33, s[0:1], 0x100
	v_lshl_add_u32 v24, v0, 2, 0
	s_mov_b32 s38, s2
	s_waitcnt lgkmcnt(0)
	v_writelane_b32 v242, s4, 0
	v_mov_b32_e32 v1, v0
	v_readfirstlane_b32 s3, v0
	s_nop 3
	s_lshr_b32 s98, s3, 6
	s_cmp_ge_u32 s98, 4
	s_cbranch_scc0 .Lprio_done
	s_setprio 1
.Lprio_done:
	v_writelane_b32 v242, s5, 1
	v_writelane_b32 v242, s6, 2
	v_writelane_b32 v242, s7, 3
	v_writelane_b32 v242, s8, 4
	v_writelane_b32 v242, s9, 5
	v_writelane_b32 v242, s10, 6
	v_writelane_b32 v242, s11, 7
	v_writelane_b32 v242, s12, 8
	v_writelane_b32 v242, s13, 9
	v_writelane_b32 v242, s14, 10
	v_writelane_b32 v242, s15, 11
	v_writelane_b32 v242, s16, 12
	v_writelane_b32 v242, s17, 13
	v_writelane_b32 v242, s18, 14
	v_writelane_b32 v242, s19, 15
	s_load_dwordx16 s[4:19], s[0:1], 0x80
	v_add_u32_e32 v2, 0x21800, v24
	v_mov_b32_e32 v3, 0
	s_waitcnt lgkmcnt(0)
	v_writelane_b32 v242, s4, 16
	s_nop 1
	v_writelane_b32 v242, s5, 17
	v_writelane_b32 v242, s6, 18
	v_writelane_b32 v242, s7, 19
	v_writelane_b32 v242, s8, 20
	v_writelane_b32 v242, s9, 21
	v_writelane_b32 v242, s10, 22
	v_writelane_b32 v242, s11, 23
	v_writelane_b32 v242, s12, 24
	v_writelane_b32 v242, s13, 25
	v_writelane_b32 v242, s14, 26
	v_writelane_b32 v242, s15, 27
	v_writelane_b32 v242, s16, 28
	v_writelane_b32 v242, s17, 29
	v_writelane_b32 v242, s18, 30
	v_writelane_b32 v242, s19, 31
	s_add_u32 s4, s0, 0x100
	s_addc_u32 s5, s1, 0
	v_writelane_b32 v242, s4, 32
	s_mov_b32 s0, 0
	s_mov_b32 s1, 1
	v_writelane_b32 v242, s5, 33
	s_mov_b64 s[4:5], 0
	s_mov_b32 s6, s0
	s_branch .LBB0_2

.LBB0_142:
	ds_read_b128 v[148:151], v154
	ds_read_b128 v[158:161], v154 offset:1024
	ds_read_b128 v[162:165], v154 offset:2048
	ds_read_b128 v[166:169], v154 offset:3072
	ds_read_b128 v[170:173], v155
	ds_read_b128 v[174:177], v155 offset:1024
	ds_read_b128 v[178:181], v155 offset:2048
	ds_read_b128 v[182:185], v155 offset:3072
	s_add_u32 s74, s72, 0xfffc0080
	s_addc_u32 s75, s73, -1
	s_cmp_eq_u32 s71, 12
	s_cselect_b32 s77, s1, s75
	s_cselect_b32 s76, s4, s74
	s_cselect_b32 s75, s5, s31
	s_cselect_b32 s74, s9, s29
	v_lshl_add_u64 v[220:221], s[72:73], 0, v[140:141]
	s_add_i32 m0, s13, 0xc000
	ds_read_b128 v[186:189], v156
	ds_read_b128 v[190:193], v156 offset:1024
	ds_read_b128 v[194:197], v156 offset:2048
	ds_read_b128 v[198:201], v156 offset:3072
	ds_read_b128 v[202:205], v156 offset:4096
	ds_read_b128 v[206:209], v156 offset:5120
	ds_read_b128 v[210:213], v156 offset:6144
	ds_read_b128 v[216:219], v156 offset:7168
	global_load_lds_dwordx4 v[220:221], off
	v_lshl_add_u64 v[220:221], s[72:73], 0, v[142:143]
	s_add_i32 m0, s13, 0xe000
	s_nop 0
	global_load_lds_dwordx4 v[220:221], off
	s_waitcnt vmcnt(8)
	s_waitcnt lgkmcnt(0)
	s_barrier
	s_waitcnt lgkmcnt(0)
	v_mfma_f32_16x16x32_bf16 v[126:129], v[148:151], v[186:189], v[126:129]
	v_mfma_f32_16x16x32_bf16 v[122:125], v[162:165], v[186:189], v[122:125]
	v_mfma_f32_16x16x32_bf16 v[110:113], v[148:151], v[194:197], v[110:113]
	v_mfma_f32_16x16x32_bf16 v[106:109], v[162:165], v[194:197], v[106:109]
	v_mfma_f32_16x16x32_bf16 v[94:97], v[148:151], v[202:205], v[94:97]
	v_mfma_f32_16x16x32_bf16 v[90:93], v[162:165], v[202:205], v[90:93]
	v_mfma_f32_16x16x32_bf16 v[78:81], v[148:151], v[210:213], v[78:81]
	v_mfma_f32_16x16x32_bf16 v[74:77], v[162:165], v[210:213], v[74:77]
	v_mfma_f32_16x16x32_bf16 v[126:129], v[158:161], v[190:193], v[126:129]
	v_mfma_f32_16x16x32_bf16 v[122:125], v[166:169], v[190:193], v[122:125]
	v_mfma_f32_16x16x32_bf16 v[110:113], v[158:161], v[198:201], v[110:113]
	v_mfma_f32_16x16x32_bf16 v[106:109], v[166:169], v[198:201], v[106:109]
	v_mfma_f32_16x16x32_bf16 v[94:97], v[158:161], v[206:209], v[94:97]
	v_mfma_f32_16x16x32_bf16 v[90:93], v[166:169], v[206:209], v[90:93]
	v_mfma_f32_16x16x32_bf16 v[78:81], v[158:161], v[216:219], v[78:81]
	v_mfma_f32_16x16x32_bf16 v[74:77], v[166:169], v[216:219], v[74:77]
	v_mfma_f32_16x16x32_bf16 v[118:121], v[170:173], v[186:189], v[118:121]
	v_mfma_f32_16x16x32_bf16 v[114:117], v[178:181], v[186:189], v[114:117]
	v_mfma_f32_16x16x32_bf16 v[102:105], v[170:173], v[194:197], v[102:105]
	v_mfma_f32_16x16x32_bf16 v[98:101], v[178:181], v[194:197], v[98:101]
	v_mfma_f32_16x16x32_bf16 v[86:89], v[170:173], v[202:205], v[86:89]
	v_mfma_f32_16x16x32_bf16 v[82:85], v[178:181], v[202:205], v[82:85]
	v_mfma_f32_16x16x32_bf16 v[70:73], v[170:173], v[210:213], v[70:73]
	v_mfma_f32_16x16x32_bf16 v[66:69], v[178:181], v[210:213], v[66:69]
	v_mfma_f32_16x16x32_bf16 v[118:121], v[174:177], v[190:193], v[118:121]
	v_mfma_f32_16x16x32_bf16 v[114:117], v[182:185], v[190:193], v[114:117]
	v_mfma_f32_16x16x32_bf16 v[102:105], v[174:177], v[198:201], v[102:105]
	v_mfma_f32_16x16x32_bf16 v[98:101], v[182:185], v[198:201], v[98:101]
	v_mfma_f32_16x16x32_bf16 v[86:89], v[174:177], v[206:209], v[86:89]
	v_mfma_f32_16x16x32_bf16 v[82:85], v[182:185], v[206:209], v[82:85]
	v_mfma_f32_16x16x32_bf16 v[70:73], v[174:177], v[216:219], v[70:73]
	v_mfma_f32_16x16x32_bf16 v[66:69], v[182:185], v[216:219], v[66:69]
	s_barrier
	s_add_i32 vcc_lo, s91, s3
	v_lshl_add_u64 v[220:221], s[74:75], 0, v[132:133]
	s_mov_b32 m0, vcc_lo
	ds_read_b128 v[186:189], v156 offset:16384
	ds_read_b128 v[190:193], v156 offset:17408
	ds_read_b128 v[194:197], v156 offset:18432
	ds_read_b128 v[198:201], v156 offset:19456
	ds_read_b128 v[202:205], v156 offset:20480
	ds_read_b128 v[206:209], v156 offset:21504
	ds_read_b128 v[210:213], v156 offset:22528
	ds_read_b128 v[216:219], v156 offset:23552
	global_load_lds_dwordx4 v[220:221], off
	s_add_i32 m0, vcc_lo, 0x2000
	s_add_u32 vcc_lo, s74, 0x40000
	v_lshl_add_u64 v[222:223], s[74:75], 0, v[136:137]
	s_addc_u32 vcc_hi, s75, 0
	s_add_i32 s88, s10, s3
	global_load_lds_dwordx4 v[222:223], off
	v_lshl_add_u64 v[224:225], vcc, 0, v[132:133]
	s_mov_b32 m0, s88
	v_lshl_add_u64 v[226:227], s[76:77], 0, v[134:135]
	global_load_lds_dwordx4 v[224:225], off
	v_lshl_add_u64 v[224:225], vcc, 0, v[136:137]
	s_add_i32 m0, s88, 0x2000
	s_nop 0
	global_load_lds_dwordx4 v[224:225], off
	v_lshl_add_u64 v[224:225], s[76:77], 0, v[130:131]
	s_mov_b32 m0, s13
	s_nop 0
	global_load_lds_dwordx4 v[224:225], off
	s_mov_b32 m0, s78
	s_nop 0
	global_load_lds_dwordx4 v[226:227], off
	s_waitcnt vmcnt(8)
	s_waitcnt lgkmcnt(0)
	s_barrier
	s_waitcnt lgkmcnt(0)
	v_mfma_f32_16x16x32_bf16 v[62:65], v[148:151], v[186:189], v[62:65]
	v_mfma_f32_16x16x32_bf16 v[58:61], v[162:165], v[186:189], v[58:61]
	v_mfma_f32_16x16x32_bf16 v[46:49], v[148:151], v[194:197], v[46:49]
	v_mfma_f32_16x16x32_bf16 v[42:45], v[162:165], v[194:197], v[42:45]
	v_mfma_f32_16x16x32_bf16 v[30:33], v[148:151], v[202:205], v[30:33]
	v_mfma_f32_16x16x32_bf16 v[26:29], v[162:165], v[202:205], v[26:29]
	v_mfma_f32_16x16x32_bf16 v[14:17], v[148:151], v[210:213], v[14:17]
	v_mfma_f32_16x16x32_bf16 v[10:13], v[162:165], v[210:213], v[10:13]
	v_mfma_f32_16x16x32_bf16 v[62:65], v[158:161], v[190:193], v[62:65]
	v_mfma_f32_16x16x32_bf16 v[58:61], v[166:169], v[190:193], v[58:61]
	v_mfma_f32_16x16x32_bf16 v[46:49], v[158:161], v[198:201], v[46:49]
	v_mfma_f32_16x16x32_bf16 v[42:45], v[166:169], v[198:201], v[42:45]
	v_mfma_f32_16x16x32_bf16 v[30:33], v[158:161], v[206:209], v[30:33]
	v_mfma_f32_16x16x32_bf16 v[26:29], v[166:169], v[206:209], v[26:29]
	v_mfma_f32_16x16x32_bf16 v[14:17], v[158:161], v[216:219], v[14:17]
	v_mfma_f32_16x16x32_bf16 v[10:13], v[166:169], v[216:219], v[10:13]
	v_mfma_f32_16x16x32_bf16 v[54:57], v[170:173], v[186:189], v[54:57]
	v_mfma_f32_16x16x32_bf16 v[50:53], v[178:181], v[186:189], v[50:53]
	v_mfma_f32_16x16x32_bf16 v[38:41], v[170:173], v[194:197], v[38:41]
	v_mfma_f32_16x16x32_bf16 v[34:37], v[178:181], v[194:197], v[34:37]
	v_mfma_f32_16x16x32_bf16 v[22:25], v[170:173], v[202:205], v[22:25]
	v_mfma_f32_16x16x32_bf16 v[18:21], v[178:181], v[202:205], v[18:21]
	v_mfma_f32_16x16x32_bf16 v[6:9], v[170:173], v[210:213], v[6:9]
	v_mfma_f32_16x16x32_bf16 v[2:5], v[178:181], v[210:213], v[2:5]
	v_mfma_f32_16x16x32_bf16 v[54:57], v[174:177], v[190:193], v[54:57]
	v_mfma_f32_16x16x32_bf16 v[50:53], v[182:185], v[190:193], v[50:53]
	v_mfma_f32_16x16x32_bf16 v[38:41], v[174:177], v[198:201], v[38:41]
	v_mfma_f32_16x16x32_bf16 v[34:37], v[182:185], v[198:201], v[34:37]
	v_mfma_f32_16x16x32_bf16 v[22:25], v[174:177], v[206:209], v[22:25]
	v_mfma_f32_16x16x32_bf16 v[18:21], v[182:185], v[206:209], v[18:21]
	v_mfma_f32_16x16x32_bf16 v[6:9], v[174:177], v[216:219], v[6:9]
	v_mfma_f32_16x16x32_bf16 v[2:5], v[182:185], v[216:219], v[2:5]
	s_barrier
	s_add_i32 s88, 0, 0x18000
	v_add_u32_e32 v157, s88, v152
	s_add_i32 s89, 0, 0x1c000
	ds_read_b128 v[148:151], v157
	ds_read_b128 v[158:161], v157 offset:1024
	ds_read_b128 v[162:165], v157 offset:2048
	ds_read_b128 v[166:169], v157 offset:3072
	v_add_u32_e32 v157, s89, v152
	ds_read_b128 v[170:173], v157
	ds_read_b128 v[174:177], v157 offset:1024
	ds_read_b128 v[178:181], v157 offset:2048
	ds_read_b128 v[182:185], v157 offset:3072
	s_add_u32 s76, s76, 0x40000
	s_addc_u32 s77, s77, 0
	s_mov_b32 m0, s79
	v_lshl_add_u64 v[228:229], s[76:77], 0, v[130:131]
	ds_read_b128 v[186:189], v156 offset:32768
	ds_read_b128 v[190:193], v156 offset:33792
	ds_read_b128 v[194:197], v156 offset:34816
	ds_read_b128 v[198:201], v156 offset:35840
	ds_read_b128 v[202:205], v156 offset:36864
	ds_read_b128 v[206:209], v156 offset:37888
	ds_read_b128 v[210:213], v156 offset:38912
	ds_read_b128 v[216:219], v156 offset:39936
	global_load_lds_dwordx4 v[228:229], off
	v_lshl_add_u64 v[228:229], s[76:77], 0, v[134:135]
	s_mov_b32 m0, s92
	s_nop 0
	global_load_lds_dwordx4 v[228:229], off
	s_waitcnt vmcnt(8)
	s_waitcnt lgkmcnt(0)
	s_barrier
	s_waitcnt lgkmcnt(0)
	v_mfma_f32_16x16x32_bf16 v[126:129], v[148:151], v[186:189], v[126:129]
	v_mfma_f32_16x16x32_bf16 v[122:125], v[162:165], v[186:189], v[122:125]
	v_mfma_f32_16x16x32_bf16 v[110:113], v[148:151], v[194:197], v[110:113]
	v_mfma_f32_16x16x32_bf16 v[106:109], v[162:165], v[194:197], v[106:109]
	v_mfma_f32_16x16x32_bf16 v[94:97], v[148:151], v[202:205], v[94:97]
	v_mfma_f32_16x16x32_bf16 v[90:93], v[162:165], v[202:205], v[90:93]
	v_mfma_f32_16x16x32_bf16 v[78:81], v[148:151], v[210:213], v[78:81]
	v_mfma_f32_16x16x32_bf16 v[74:77], v[162:165], v[210:213], v[74:77]
	v_mfma_f32_16x16x32_bf16 v[126:129], v[158:161], v[190:193], v[126:129]
	v_mfma_f32_16x16x32_bf16 v[122:125], v[166:169], v[190:193], v[122:125]
	v_mfma_f32_16x16x32_bf16 v[110:113], v[158:161], v[198:201], v[110:113]
	v_mfma_f32_16x16x32_bf16 v[106:109], v[166:169], v[198:201], v[106:109]
	v_mfma_f32_16x16x32_bf16 v[94:97], v[158:161], v[206:209], v[94:97]
	v_mfma_f32_16x16x32_bf16 v[90:93], v[166:169], v[206:209], v[90:93]
	v_mfma_f32_16x16x32_bf16 v[78:81], v[158:161], v[216:219], v[78:81]
	v_mfma_f32_16x16x32_bf16 v[74:77], v[166:169], v[216:219], v[74:77]
	v_mfma_f32_16x16x32_bf16 v[118:121], v[170:173], v[186:189], v[118:121]
	v_mfma_f32_16x16x32_bf16 v[114:117], v[178:181], v[186:189], v[114:117]
	v_mfma_f32_16x16x32_bf16 v[102:105], v[170:173], v[194:197], v[102:105]
	v_mfma_f32_16x16x32_bf16 v[98:101], v[178:181], v[194:197], v[98:101]
	v_mfma_f32_16x16x32_bf16 v[86:89], v[170:173], v[202:205], v[86:89]
	v_mfma_f32_16x16x32_bf16 v[82:85], v[178:181], v[202:205], v[82:85]
	v_mfma_f32_16x16x32_bf16 v[70:73], v[170:173], v[210:213], v[70:73]
	v_mfma_f32_16x16x32_bf16 v[66:69], v[178:181], v[210:213], v[66:69]
	v_mfma_f32_16x16x32_bf16 v[118:121], v[174:177], v[190:193], v[118:121]
	v_mfma_f32_16x16x32_bf16 v[114:117], v[182:185], v[190:193], v[114:117]
	v_mfma_f32_16x16x32_bf16 v[102:105], v[174:177], v[198:201], v[102:105]
	v_mfma_f32_16x16x32_bf16 v[98:101], v[182:185], v[198:201], v[98:101]
	v_mfma_f32_16x16x32_bf16 v[86:89], v[174:177], v[206:209], v[86:89]
	v_mfma_f32_16x16x32_bf16 v[82:85], v[182:185], v[206:209], v[82:85]
	v_mfma_f32_16x16x32_bf16 v[70:73], v[174:177], v[216:219], v[70:73]
	v_mfma_f32_16x16x32_bf16 v[66:69], v[182:185], v[216:219], v[66:69]
	s_barrier
	s_add_i32 s76, s88, s3
	v_lshl_add_u64 v[220:221], v[220:221], 0, s[24:25]
	s_mov_b32 m0, s76
	ds_read_b128 v[186:189], v156 offset:49152
	ds_read_b128 v[190:193], v156 offset:50176
	ds_read_b128 v[194:197], v156 offset:51200
	ds_read_b128 v[198:201], v156 offset:52224
	ds_read_b128 v[202:205], v156 offset:53248
	ds_read_b128 v[206:209], v156 offset:54272
	ds_read_b128 v[210:213], v156 offset:55296
	ds_read_b128 v[216:219], v156 offset:56320
	global_load_lds_dwordx4 v[220:221], off
	s_add_i32 m0, s76, 0x2000
	s_add_u32 s74, s74, 0x40080
	v_lshl_add_u64 v[220:221], v[222:223], 0, s[24:25]
	s_addc_u32 s75, s75, 0
	s_add_i32 s76, s89, s3
	global_load_lds_dwordx4 v[220:221], off
	v_lshl_add_u64 v[220:221], s[74:75], 0, v[132:133]
	s_mov_b32 m0, s76
	s_nop 0
	global_load_lds_dwordx4 v[220:221], off
	v_lshl_add_u64 v[220:221], s[74:75], 0, v[136:137]
	s_add_i32 m0, s76, 0x2000
	s_nop 0
	global_load_lds_dwordx4 v[220:221], off
	v_lshl_add_u64 v[220:221], v[224:225], 0, s[24:25]
	s_mov_b32 m0, s94
	s_nop 0
	global_load_lds_dwordx4 v[220:221], off
	v_lshl_add_u64 v[220:221], v[226:227], 0, s[24:25]
	s_mov_b32 m0, s95
	s_nop 0
	global_load_lds_dwordx4 v[220:221], off
	s_waitcnt vmcnt(8)
	s_waitcnt lgkmcnt(0)
	s_barrier
	s_waitcnt lgkmcnt(0)
	v_mfma_f32_16x16x32_bf16 v[62:65], v[148:151], v[186:189], v[62:65]
	v_mfma_f32_16x16x32_bf16 v[58:61], v[162:165], v[186:189], v[58:61]
	v_mfma_f32_16x16x32_bf16 v[46:49], v[148:151], v[194:197], v[46:49]
	v_mfma_f32_16x16x32_bf16 v[42:45], v[162:165], v[194:197], v[42:45]
	v_mfma_f32_16x16x32_bf16 v[30:33], v[148:151], v[202:205], v[30:33]
	v_mfma_f32_16x16x32_bf16 v[26:29], v[162:165], v[202:205], v[26:29]
	v_mfma_f32_16x16x32_bf16 v[14:17], v[148:151], v[210:213], v[14:17]
	v_mfma_f32_16x16x32_bf16 v[10:13], v[162:165], v[210:213], v[10:13]
	v_mfma_f32_16x16x32_bf16 v[62:65], v[158:161], v[190:193], v[62:65]
	v_mfma_f32_16x16x32_bf16 v[58:61], v[166:169], v[190:193], v[58:61]
	v_mfma_f32_16x16x32_bf16 v[46:49], v[158:161], v[198:201], v[46:49]
	v_mfma_f32_16x16x32_bf16 v[42:45], v[166:169], v[198:201], v[42:45]
	v_mfma_f32_16x16x32_bf16 v[30:33], v[158:161], v[206:209], v[30:33]
	v_mfma_f32_16x16x32_bf16 v[26:29], v[166:169], v[206:209], v[26:29]
	v_mfma_f32_16x16x32_bf16 v[14:17], v[158:161], v[216:219], v[14:17]
	v_mfma_f32_16x16x32_bf16 v[10:13], v[166:169], v[216:219], v[10:13]
	v_mfma_f32_16x16x32_bf16 v[54:57], v[170:173], v[186:189], v[54:57]
	v_mfma_f32_16x16x32_bf16 v[50:53], v[178:181], v[186:189], v[50:53]
	v_mfma_f32_16x16x32_bf16 v[38:41], v[170:173], v[194:197], v[38:41]
	v_mfma_f32_16x16x32_bf16 v[34:37], v[178:181], v[194:197], v[34:37]
	v_mfma_f32_16x16x32_bf16 v[22:25], v[170:173], v[202:205], v[22:25]
	v_mfma_f32_16x16x32_bf16 v[18:21], v[178:181], v[202:205], v[18:21]
	v_mfma_f32_16x16x32_bf16 v[6:9], v[170:173], v[210:213], v[6:9]
	v_mfma_f32_16x16x32_bf16 v[2:5], v[178:181], v[210:213], v[2:5]
	v_mfma_f32_16x16x32_bf16 v[54:57], v[174:177], v[190:193], v[54:57]
	v_mfma_f32_16x16x32_bf16 v[50:53], v[182:185], v[190:193], v[50:53]
	v_mfma_f32_16x16x32_bf16 v[38:41], v[174:177], v[198:201], v[38:41]
	v_mfma_f32_16x16x32_bf16 v[34:37], v[182:185], v[198:201], v[34:37]
	v_mfma_f32_16x16x32_bf16 v[22:25], v[174:177], v[206:209], v[22:25]
	v_mfma_f32_16x16x32_bf16 v[18:21], v[182:185], v[206:209], v[18:21]
	v_mfma_f32_16x16x32_bf16 v[6:9], v[174:177], v[216:219], v[6:9]
	v_mfma_f32_16x16x32_bf16 v[2:5], v[182:185], v[216:219], v[2:5]
	s_barrier
	s_add_i32 s71, s71, 2
	s_add_u32 s72, s72, 0x100
	s_addc_u32 s73, s73, 0
	s_add_u32 s29, s29, 0x100
	s_addc_u32 s31, s31, 0
	s_cmp_gt_u32 s71, 13
	s_cbranch_scc0 .LBB0_142
	s_and_b64 vcc, exec, s[26:27]
	s_cbranch_vccz .LBB0_145
	s_barrier

.LBB0_382:
	ds_read_b128 v[148:151], v79
	ds_read_b128 v[152:155], v79 offset:1024
	ds_read_b128 v[156:159], v79 offset:2048
	ds_read_b128 v[160:163], v79 offset:3072
	ds_read_b128 v[164:167], v80
	ds_read_b128 v[168:171], v80 offset:1024
	ds_read_b128 v[172:175], v80 offset:2048
	ds_read_b128 v[176:179], v80 offset:3072
	s_add_u32 s20, s16, s18
	s_addc_u32 s21, s17, s19
	s_add_u32 s20, s20, 0xd000100
	s_addc_u32 s21, s21, 0
	s_add_u32 s74, s29, s18
	s_addc_u32 s75, s30, s19
	s_cmpk_eq_i32 s18, 0x300
	s_cselect_b32 s23, s11, s21
	s_cselect_b32 s22, s10, s20
	s_cselect_b32 s21, s9, s75
	s_cselect_b32 s20, s8, s74
	s_mov_b32 m0, s34
	v_lshl_add_u64 v[212:213], v[74:75], 0, s[18:19]
	ds_read_b128 v[180:183], v81
	ds_read_b128 v[184:187], v81 offset:1024
	ds_read_b128 v[188:191], v81 offset:2048
	ds_read_b128 v[192:195], v81 offset:3072
	ds_read_b128 v[196:199], v81 offset:4096
	ds_read_b128 v[200:203], v81 offset:5120
	global_load_lds_dwordx4 v[212:213], off
	v_lshl_add_u64 v[212:213], v[76:77], 0, s[18:19]
	s_mov_b32 m0, s35
	s_nop 0
	global_load_lds_dwordx4 v[212:213], off
	s_waitcnt vmcnt(8)
	s_waitcnt lgkmcnt(0)
	s_barrier
	s_waitcnt lgkmcnt(0)
	v_mfma_f32_16x16x32_bf16 v[142:145], v[148:151], v[180:183], v[142:145]
	v_mfma_f32_16x16x32_bf16 v[138:141], v[156:159], v[180:183], v[138:141]
	v_mfma_f32_16x16x32_bf16 v[126:129], v[148:151], v[188:191], v[126:129]
	v_mfma_f32_16x16x32_bf16 v[122:125], v[156:159], v[188:191], v[122:125]
	v_mfma_f32_16x16x32_bf16 v[110:113], v[148:151], v[196:199], v[110:113]
	v_mfma_f32_16x16x32_bf16 v[106:109], v[156:159], v[196:199], v[106:109]
	v_mfma_f32_16x16x32_bf16 v[142:145], v[152:155], v[184:187], v[142:145]
	v_mfma_f32_16x16x32_bf16 v[138:141], v[160:163], v[184:187], v[138:141]
	v_mfma_f32_16x16x32_bf16 v[126:129], v[152:155], v[192:195], v[126:129]
	v_mfma_f32_16x16x32_bf16 v[122:125], v[160:163], v[192:195], v[122:125]
	v_mfma_f32_16x16x32_bf16 v[110:113], v[152:155], v[200:203], v[110:113]
	v_mfma_f32_16x16x32_bf16 v[106:109], v[160:163], v[200:203], v[106:109]
	v_mfma_f32_16x16x32_bf16 v[134:137], v[164:167], v[180:183], v[134:137]
	v_mfma_f32_16x16x32_bf16 v[130:133], v[172:175], v[180:183], v[130:133]
	v_mfma_f32_16x16x32_bf16 v[118:121], v[164:167], v[188:191], v[118:121]
	v_mfma_f32_16x16x32_bf16 v[114:117], v[172:175], v[188:191], v[114:117]
	v_mfma_f32_16x16x32_bf16 v[102:105], v[164:167], v[196:199], v[102:105]
	v_mfma_f32_16x16x32_bf16 v[98:101], v[172:175], v[196:199], v[98:101]
	v_mfma_f32_16x16x32_bf16 v[134:137], v[168:171], v[184:187], v[134:137]
	v_mfma_f32_16x16x32_bf16 v[130:133], v[176:179], v[184:187], v[130:133]
	v_mfma_f32_16x16x32_bf16 v[118:121], v[168:171], v[192:195], v[118:121]
	v_mfma_f32_16x16x32_bf16 v[114:117], v[176:179], v[192:195], v[114:117]
	v_mfma_f32_16x16x32_bf16 v[102:105], v[168:171], v[200:203], v[102:105]
	v_mfma_f32_16x16x32_bf16 v[98:101], v[176:179], v[200:203], v[98:101]
	s_barrier
	s_mov_b32 m0, s36
	v_lshl_add_u64 v[212:213], s[20:21], 0, v[62:63]
	s_add_u32 s74, s20, 0x20000
	ds_read_b128 v[180:183], v81 offset:16384
	ds_read_b128 v[184:187], v81 offset:17408
	ds_read_b128 v[188:191], v81 offset:18432
	ds_read_b128 v[192:195], v81 offset:19456
	ds_read_b128 v[196:199], v81 offset:20480
	ds_read_b128 v[200:203], v81 offset:21504
	global_load_lds_dwordx4 v[212:213], off
	v_lshl_add_u64 v[216:217], s[20:21], 0, v[58:59]
	s_mov_b32 m0, s37
	s_addc_u32 s75, s21, 0
	global_load_lds_dwordx4 v[216:217], off
	v_lshl_add_u64 v[218:219], s[74:75], 0, v[62:63]
	s_mov_b32 m0, s62
	v_lshl_add_u64 v[220:221], s[22:23], 0, v[60:61]
	global_load_lds_dwordx4 v[218:219], off
	v_lshl_add_u64 v[218:219], s[74:75], 0, v[58:59]
	s_mov_b32 m0, s63
	s_nop 0
	global_load_lds_dwordx4 v[218:219], off
	v_lshl_add_u64 v[218:219], s[22:23], 0, v[64:65]
	s_mov_b32 m0, s4
	s_nop 0
	global_load_lds_dwordx4 v[218:219], off
	s_mov_b32 m0, s5
	s_nop 0
	global_load_lds_dwordx4 v[220:221], off
	s_waitcnt vmcnt(8)
	s_waitcnt lgkmcnt(0)
	s_barrier
	s_waitcnt lgkmcnt(0)
	v_mfma_f32_16x16x32_bf16 v[70:73], v[148:151], v[180:183], v[70:73]
	v_mfma_f32_16x16x32_bf16 v[66:69], v[156:159], v[180:183], v[66:69]
	v_mfma_f32_16x16x32_bf16 v[46:49], v[148:151], v[188:191], v[46:49]
	v_mfma_f32_16x16x32_bf16 v[42:45], v[156:159], v[188:191], v[42:45]
	v_mfma_f32_16x16x32_bf16 v[30:33], v[148:151], v[196:199], v[30:33]
	v_mfma_f32_16x16x32_bf16 v[26:29], v[156:159], v[196:199], v[26:29]
	v_mfma_f32_16x16x32_bf16 v[70:73], v[152:155], v[184:187], v[70:73]
	v_mfma_f32_16x16x32_bf16 v[66:69], v[160:163], v[184:187], v[66:69]
	v_mfma_f32_16x16x32_bf16 v[46:49], v[152:155], v[192:195], v[46:49]
	v_mfma_f32_16x16x32_bf16 v[42:45], v[160:163], v[192:195], v[42:45]
	v_mfma_f32_16x16x32_bf16 v[30:33], v[152:155], v[200:203], v[30:33]
	v_mfma_f32_16x16x32_bf16 v[26:29], v[160:163], v[200:203], v[26:29]
	v_mfma_f32_16x16x32_bf16 v[54:57], v[164:167], v[180:183], v[54:57]
	v_mfma_f32_16x16x32_bf16 v[50:53], v[172:175], v[180:183], v[50:53]
	v_mfma_f32_16x16x32_bf16 v[38:41], v[164:167], v[188:191], v[38:41]
	v_mfma_f32_16x16x32_bf16 v[34:37], v[172:175], v[188:191], v[34:37]
	v_mfma_f32_16x16x32_bf16 v[22:25], v[164:167], v[196:199], v[22:25]
	v_mfma_f32_16x16x32_bf16 v[18:21], v[172:175], v[196:199], v[18:21]
	v_mfma_f32_16x16x32_bf16 v[54:57], v[168:171], v[184:187], v[54:57]
	v_mfma_f32_16x16x32_bf16 v[50:53], v[176:179], v[184:187], v[50:53]
	v_mfma_f32_16x16x32_bf16 v[38:41], v[168:171], v[192:195], v[38:41]
	v_mfma_f32_16x16x32_bf16 v[34:37], v[176:179], v[192:195], v[34:37]
	v_mfma_f32_16x16x32_bf16 v[22:25], v[168:171], v[200:203], v[22:25]
	v_mfma_f32_16x16x32_bf16 v[18:21], v[176:179], v[200:203], v[18:21]
	s_barrier
	ds_read_b128 v[148:151], v146
	ds_read_b128 v[152:155], v146 offset:1024
	ds_read_b128 v[156:159], v146 offset:2048
	ds_read_b128 v[160:163], v146 offset:3072
	ds_read_b128 v[164:167], v147
	ds_read_b128 v[168:171], v147 offset:1024
	ds_read_b128 v[172:175], v147 offset:2048
	ds_read_b128 v[176:179], v147 offset:3072
	s_add_u32 s22, s22, 0x18000
	s_addc_u32 s23, s23, 0
	s_mov_b32 m0, s24
	v_lshl_add_u64 v[222:223], s[22:23], 0, v[64:65]
	ds_read_b128 v[180:183], v81 offset:32768
	ds_read_b128 v[184:187], v81 offset:33792
	ds_read_b128 v[188:191], v81 offset:34816
	ds_read_b128 v[192:195], v81 offset:35840
	ds_read_b128 v[196:199], v81 offset:36864
	ds_read_b128 v[200:203], v81 offset:37888
	global_load_lds_dwordx4 v[222:223], off
	v_lshl_add_u64 v[222:223], s[22:23], 0, v[60:61]
	s_mov_b32 m0, s25
	s_nop 0
	global_load_lds_dwordx4 v[222:223], off
	s_waitcnt vmcnt(8)
	s_waitcnt lgkmcnt(0)
	s_barrier
	s_waitcnt lgkmcnt(0)
	v_mfma_f32_16x16x32_bf16 v[142:145], v[148:151], v[180:183], v[142:145]
	v_mfma_f32_16x16x32_bf16 v[138:141], v[156:159], v[180:183], v[138:141]
	v_mfma_f32_16x16x32_bf16 v[126:129], v[148:151], v[188:191], v[126:129]
	v_mfma_f32_16x16x32_bf16 v[122:125], v[156:159], v[188:191], v[122:125]
	v_mfma_f32_16x16x32_bf16 v[110:113], v[148:151], v[196:199], v[110:113]
	v_mfma_f32_16x16x32_bf16 v[106:109], v[156:159], v[196:199], v[106:109]
	v_mfma_f32_16x16x32_bf16 v[142:145], v[152:155], v[184:187], v[142:145]
	v_mfma_f32_16x16x32_bf16 v[138:141], v[160:163], v[184:187], v[138:141]
	v_mfma_f32_16x16x32_bf16 v[126:129], v[152:155], v[192:195], v[126:129]
	v_mfma_f32_16x16x32_bf16 v[122:125], v[160:163], v[192:195], v[122:125]
	v_mfma_f32_16x16x32_bf16 v[110:113], v[152:155], v[200:203], v[110:113]
	v_mfma_f32_16x16x32_bf16 v[106:109], v[160:163], v[200:203], v[106:109]
	v_mfma_f32_16x16x32_bf16 v[134:137], v[164:167], v[180:183], v[134:137]
	v_mfma_f32_16x16x32_bf16 v[130:133], v[172:175], v[180:183], v[130:133]
	v_mfma_f32_16x16x32_bf16 v[118:121], v[164:167], v[188:191], v[118:121]
	v_mfma_f32_16x16x32_bf16 v[114:117], v[172:175], v[188:191], v[114:117]
	v_mfma_f32_16x16x32_bf16 v[102:105], v[164:167], v[196:199], v[102:105]
	v_mfma_f32_16x16x32_bf16 v[98:101], v[172:175], v[196:199], v[98:101]
	v_mfma_f32_16x16x32_bf16 v[134:137], v[168:171], v[184:187], v[134:137]
	v_mfma_f32_16x16x32_bf16 v[130:133], v[176:179], v[184:187], v[130:133]
	v_mfma_f32_16x16x32_bf16 v[118:121], v[168:171], v[192:195], v[118:121]
	v_mfma_f32_16x16x32_bf16 v[114:117], v[176:179], v[192:195], v[114:117]
	v_mfma_f32_16x16x32_bf16 v[102:105], v[168:171], v[200:203], v[102:105]
	v_mfma_f32_16x16x32_bf16 v[98:101], v[176:179], v[200:203], v[98:101]
	s_barrier
	s_mov_b32 m0, s64
	v_lshl_add_u64 v[212:213], v[212:213], 0, s[14:15]
	s_add_u32 s20, s20, 0x20080
	ds_read_b128 v[180:183], v81 offset:49152
	ds_read_b128 v[184:187], v81 offset:50176
	ds_read_b128 v[188:191], v81 offset:51200
	ds_read_b128 v[192:195], v81 offset:52224
	ds_read_b128 v[196:199], v81 offset:53248
	ds_read_b128 v[200:203], v81 offset:54272
	global_load_lds_dwordx4 v[212:213], off
	v_lshl_add_u64 v[212:213], v[216:217], 0, s[14:15]
	s_mov_b32 m0, s65
	s_addc_u32 s21, s21, 0
	global_load_lds_dwordx4 v[212:213], off
	v_lshl_add_u64 v[212:213], s[20:21], 0, v[62:63]
	s_mov_b32 m0, s72
	s_nop 0
	global_load_lds_dwordx4 v[212:213], off
	v_lshl_add_u64 v[212:213], s[20:21], 0, v[58:59]
	s_mov_b32 m0, s73
	s_nop 0
	global_load_lds_dwordx4 v[212:213], off
	v_lshl_add_u64 v[212:213], v[218:219], 0, s[14:15]
	s_mov_b32 m0, s27
	s_nop 0
	global_load_lds_dwordx4 v[212:213], off
	v_lshl_add_u64 v[212:213], v[220:221], 0, s[14:15]
	s_mov_b32 m0, s28
	s_nop 0
	global_load_lds_dwordx4 v[212:213], off
	s_waitcnt vmcnt(8)
	s_waitcnt lgkmcnt(0)
	s_barrier
	s_waitcnt lgkmcnt(0)
	v_mfma_f32_16x16x32_bf16 v[70:73], v[148:151], v[180:183], v[70:73]
	v_mfma_f32_16x16x32_bf16 v[66:69], v[156:159], v[180:183], v[66:69]
	v_mfma_f32_16x16x32_bf16 v[46:49], v[148:151], v[188:191], v[46:49]
	v_mfma_f32_16x16x32_bf16 v[42:45], v[156:159], v[188:191], v[42:45]
	v_mfma_f32_16x16x32_bf16 v[30:33], v[148:151], v[196:199], v[30:33]
	v_mfma_f32_16x16x32_bf16 v[26:29], v[156:159], v[196:199], v[26:29]
	v_mfma_f32_16x16x32_bf16 v[70:73], v[152:155], v[184:187], v[70:73]
	v_mfma_f32_16x16x32_bf16 v[66:69], v[160:163], v[184:187], v[66:69]
	v_mfma_f32_16x16x32_bf16 v[46:49], v[152:155], v[192:195], v[46:49]
	v_mfma_f32_16x16x32_bf16 v[42:45], v[160:163], v[192:195], v[42:45]
	v_mfma_f32_16x16x32_bf16 v[30:33], v[152:155], v[200:203], v[30:33]
	v_mfma_f32_16x16x32_bf16 v[26:29], v[160:163], v[200:203], v[26:29]
	v_mfma_f32_16x16x32_bf16 v[54:57], v[164:167], v[180:183], v[54:57]
	v_mfma_f32_16x16x32_bf16 v[50:53], v[172:175], v[180:183], v[50:53]
	v_mfma_f32_16x16x32_bf16 v[38:41], v[164:167], v[188:191], v[38:41]
	v_mfma_f32_16x16x32_bf16 v[34:37], v[172:175], v[188:191], v[34:37]
	v_mfma_f32_16x16x32_bf16 v[22:25], v[164:167], v[196:199], v[22:25]
	v_mfma_f32_16x16x32_bf16 v[18:21], v[172:175], v[196:199], v[18:21]
	v_mfma_f32_16x16x32_bf16 v[54:57], v[168:171], v[184:187], v[54:57]
	v_mfma_f32_16x16x32_bf16 v[50:53], v[176:179], v[184:187], v[50:53]
	v_mfma_f32_16x16x32_bf16 v[38:41], v[168:171], v[192:195], v[38:41]
	v_mfma_f32_16x16x32_bf16 v[34:37], v[176:179], v[192:195], v[34:37]
	v_mfma_f32_16x16x32_bf16 v[22:25], v[168:171], v[200:203], v[22:25]
	v_mfma_f32_16x16x32_bf16 v[18:21], v[176:179], v[200:203], v[18:21]
	s_barrier
	s_add_i32 s31, s31, 2
	s_add_u32 s18, s18, 0x100
	s_addc_u32 s19, s19, 0
	s_cmp_gt_u32 s31, 5
	s_cbranch_scc0 .LBB0_382
	s_cmpk_lt_u32 s0, 0x100
	s_cbranch_scc0 .LBB0_385
	s_barrier

.LBB0_451:
	v_add_u32_e32 v153, s74, v151
	ds_read_b128 v[154:157], v153
	ds_read_b128 v[158:161], v153 offset:1024
	ds_read_b128 v[162:165], v153 offset:2048
	ds_read_b128 v[166:169], v153 offset:3072
	v_add_u32_e32 v153, s75, v151
	s_add_u32 s28, s10, s26
	ds_read_b128 v[170:173], v153
	ds_read_b128 v[174:177], v153 offset:1024
	ds_read_b128 v[178:181], v153 offset:2048
	ds_read_b128 v[182:185], v153 offset:3072
	s_addc_u32 s29, s11, s27
	s_add_u32 s28, s28, 0x100
	s_addc_u32 s29, s29, 0
	s_add_u32 s80, s4, s26
	s_addc_u32 s81, s5, s27
	s_cmpk_eq_i32 s26, 0x700
	s_cselect_b32 s31, s21, s29
	s_cselect_b32 s30, s77, s28
	s_cselect_b32 s29, s19, s81
	s_cselect_b32 s28, s78, s80
	v_lshl_add_u64 v[222:223], v[146:147], 0, s[26:27]
	s_add_i32 m0, s63, 0xc000
	ds_read_b128 v[186:189], v152
	ds_read_b128 v[190:193], v152 offset:1024
	ds_read_b128 v[194:197], v152 offset:2048
	ds_read_b128 v[198:201], v152 offset:3072
	ds_read_b128 v[202:205], v152 offset:4096
	ds_read_b128 v[206:209], v152 offset:5120
	ds_read_b128 v[210:213], v152 offset:6144
	ds_read_b128 v[218:221], v152 offset:7168
	global_load_lds_dwordx4 v[222:223], off
	v_lshl_add_u64 v[222:223], v[148:149], 0, s[26:27]
	s_add_i32 m0, s63, 0xe000
	s_nop 0
	global_load_lds_dwordx4 v[222:223], off
	s_waitcnt vmcnt(8)
	s_waitcnt lgkmcnt(0)
	s_barrier
	s_waitcnt lgkmcnt(0)
	v_mfma_f32_16x16x32_bf16 v[126:129], v[154:157], v[186:189], v[126:129]
	v_mfma_f32_16x16x32_bf16 v[122:125], v[162:165], v[186:189], v[122:125]
	v_mfma_f32_16x16x32_bf16 v[118:121], v[154:157], v[194:197], v[118:121]
	v_mfma_f32_16x16x32_bf16 v[114:117], v[162:165], v[194:197], v[114:117]
	v_mfma_f32_16x16x32_bf16 v[94:97], v[154:157], v[202:205], v[94:97]
	v_mfma_f32_16x16x32_bf16 v[90:93], v[162:165], v[202:205], v[90:93]
	v_mfma_f32_16x16x32_bf16 v[78:81], v[154:157], v[210:213], v[78:81]
	v_mfma_f32_16x16x32_bf16 v[74:77], v[162:165], v[210:213], v[74:77]
	v_mfma_f32_16x16x32_bf16 v[126:129], v[158:161], v[190:193], v[126:129]
	v_mfma_f32_16x16x32_bf16 v[122:125], v[166:169], v[190:193], v[122:125]
	v_mfma_f32_16x16x32_bf16 v[118:121], v[158:161], v[198:201], v[118:121]
	v_mfma_f32_16x16x32_bf16 v[114:117], v[166:169], v[198:201], v[114:117]
	v_mfma_f32_16x16x32_bf16 v[94:97], v[158:161], v[206:209], v[94:97]
	v_mfma_f32_16x16x32_bf16 v[90:93], v[166:169], v[206:209], v[90:93]
	v_mfma_f32_16x16x32_bf16 v[78:81], v[158:161], v[218:221], v[78:81]
	v_mfma_f32_16x16x32_bf16 v[74:77], v[166:169], v[218:221], v[74:77]
	v_mfma_f32_16x16x32_bf16 v[110:113], v[170:173], v[186:189], v[110:113]
	v_mfma_f32_16x16x32_bf16 v[106:109], v[178:181], v[186:189], v[106:109]
	v_mfma_f32_16x16x32_bf16 v[102:105], v[170:173], v[194:197], v[102:105]
	v_mfma_f32_16x16x32_bf16 v[98:101], v[178:181], v[194:197], v[98:101]
	v_mfma_f32_16x16x32_bf16 v[86:89], v[170:173], v[202:205], v[86:89]
	v_mfma_f32_16x16x32_bf16 v[82:85], v[178:181], v[202:205], v[82:85]
	v_mfma_f32_16x16x32_bf16 v[70:73], v[170:173], v[210:213], v[70:73]
	v_mfma_f32_16x16x32_bf16 v[66:69], v[178:181], v[210:213], v[66:69]
	v_mfma_f32_16x16x32_bf16 v[110:113], v[174:177], v[190:193], v[110:113]
	v_mfma_f32_16x16x32_bf16 v[106:109], v[182:185], v[190:193], v[106:109]
	v_mfma_f32_16x16x32_bf16 v[102:105], v[174:177], v[198:201], v[102:105]
	v_mfma_f32_16x16x32_bf16 v[98:101], v[182:185], v[198:201], v[98:101]
	v_mfma_f32_16x16x32_bf16 v[86:89], v[174:177], v[206:209], v[86:89]
	v_mfma_f32_16x16x32_bf16 v[82:85], v[182:185], v[206:209], v[82:85]
	v_mfma_f32_16x16x32_bf16 v[70:73], v[174:177], v[218:221], v[70:73]
	v_mfma_f32_16x16x32_bf16 v[66:69], v[182:185], v[218:221], v[66:69]
	s_barrier
	s_add_i32 s80, s74, s37
	v_lshl_add_u64 v[222:223], s[28:29], 0, v[134:135]
	s_mov_b32 m0, s80
	ds_read_b128 v[186:189], v152 offset:16384
	ds_read_b128 v[190:193], v152 offset:17408
	ds_read_b128 v[194:197], v152 offset:18432
	ds_read_b128 v[198:201], v152 offset:19456
	ds_read_b128 v[202:205], v152 offset:20480
	ds_read_b128 v[206:209], v152 offset:21504
	ds_read_b128 v[210:213], v152 offset:22528
	ds_read_b128 v[218:221], v152 offset:23552
	global_load_lds_dwordx4 v[222:223], off
	s_add_i32 m0, s80, 0x2000
	s_add_u32 s80, s28, 0x40000
	v_lshl_add_u64 v[224:225], s[28:29], 0, v[130:131]
	s_addc_u32 s81, s29, 0
	s_add_i32 s88, s75, s37
	global_load_lds_dwordx4 v[224:225], off
	v_lshl_add_u64 v[226:227], s[80:81], 0, v[134:135]
	s_mov_b32 m0, s88
	v_lshl_add_u64 v[228:229], s[30:31], 0, v[132:133]
	global_load_lds_dwordx4 v[226:227], off
	v_lshl_add_u64 v[226:227], s[80:81], 0, v[130:131]
	s_add_i32 m0, s88, 0x2000
	s_nop 0
	global_load_lds_dwordx4 v[226:227], off
	v_lshl_add_u64 v[226:227], s[30:31], 0, v[136:137]
	s_mov_b32 m0, s63
	s_nop 0
	global_load_lds_dwordx4 v[226:227], off
	s_mov_b32 m0, s0
	s_nop 0
	global_load_lds_dwordx4 v[228:229], off
	s_waitcnt vmcnt(8)
	s_waitcnt lgkmcnt(0)
	s_barrier
	s_waitcnt lgkmcnt(0)
	v_mfma_f32_16x16x32_bf16 v[62:65], v[154:157], v[186:189], v[62:65]
	v_mfma_f32_16x16x32_bf16 v[58:61], v[162:165], v[186:189], v[58:61]
	v_mfma_f32_16x16x32_bf16 v[50:53], v[154:157], v[194:197], v[50:53]
	v_mfma_f32_16x16x32_bf16 v[42:45], v[162:165], v[194:197], v[42:45]
	v_mfma_f32_16x16x32_bf16 v[30:33], v[154:157], v[202:205], v[30:33]
	v_mfma_f32_16x16x32_bf16 v[26:29], v[162:165], v[202:205], v[26:29]
	v_mfma_f32_16x16x32_bf16 v[22:25], v[154:157], v[210:213], v[22:25]
	v_mfma_f32_16x16x32_bf16 v[18:21], v[162:165], v[210:213], v[18:21]
	v_mfma_f32_16x16x32_bf16 v[62:65], v[158:161], v[190:193], v[62:65]
	v_mfma_f32_16x16x32_bf16 v[58:61], v[166:169], v[190:193], v[58:61]
	v_mfma_f32_16x16x32_bf16 v[50:53], v[158:161], v[198:201], v[50:53]
	v_mfma_f32_16x16x32_bf16 v[42:45], v[166:169], v[198:201], v[42:45]
	v_mfma_f32_16x16x32_bf16 v[30:33], v[158:161], v[206:209], v[30:33]
	v_mfma_f32_16x16x32_bf16 v[26:29], v[166:169], v[206:209], v[26:29]
	v_mfma_f32_16x16x32_bf16 v[22:25], v[158:161], v[218:221], v[22:25]
	v_mfma_f32_16x16x32_bf16 v[18:21], v[166:169], v[218:221], v[18:21]
	v_mfma_f32_16x16x32_bf16 v[54:57], v[170:173], v[186:189], v[54:57]
	v_mfma_f32_16x16x32_bf16 v[46:49], v[178:181], v[186:189], v[46:49]
	v_mfma_f32_16x16x32_bf16 v[38:41], v[170:173], v[194:197], v[38:41]
	v_mfma_f32_16x16x32_bf16 v[34:37], v[178:181], v[194:197], v[34:37]
	v_mfma_f32_16x16x32_bf16 v[14:17], v[170:173], v[202:205], v[14:17]
	v_mfma_f32_16x16x32_bf16 v[10:13], v[178:181], v[202:205], v[10:13]
	v_mfma_f32_16x16x32_bf16 v[6:9], v[170:173], v[210:213], v[6:9]
	v_mfma_f32_16x16x32_bf16 v[2:5], v[178:181], v[210:213], v[2:5]
	v_mfma_f32_16x16x32_bf16 v[54:57], v[174:177], v[190:193], v[54:57]
	v_mfma_f32_16x16x32_bf16 v[46:49], v[182:185], v[190:193], v[46:49]
	v_mfma_f32_16x16x32_bf16 v[38:41], v[174:177], v[198:201], v[38:41]
	v_mfma_f32_16x16x32_bf16 v[34:37], v[182:185], v[198:201], v[34:37]
	v_mfma_f32_16x16x32_bf16 v[14:17], v[174:177], v[206:209], v[14:17]
	v_mfma_f32_16x16x32_bf16 v[10:13], v[182:185], v[206:209], v[10:13]
	v_mfma_f32_16x16x32_bf16 v[6:9], v[174:177], v[218:221], v[6:9]
	v_mfma_f32_16x16x32_bf16 v[2:5], v[182:185], v[218:221], v[2:5]
	s_barrier
	s_add_i32 s80, 0, 0x18000
	v_add_u32_e32 v153, s80, v151
	s_add_i32 s81, 0, 0x1c000
	ds_read_b128 v[154:157], v153
	ds_read_b128 v[158:161], v153 offset:1024
	ds_read_b128 v[162:165], v153 offset:2048
	ds_read_b128 v[166:169], v153 offset:3072
	v_add_u32_e32 v153, s81, v151
	ds_read_b128 v[170:173], v153
	ds_read_b128 v[174:177], v153 offset:1024
	ds_read_b128 v[178:181], v153 offset:2048
	ds_read_b128 v[182:185], v153 offset:3072
	s_add_u32 s30, s30, 0x40000
	s_addc_u32 s31, s31, 0
	s_mov_b32 m0, s1
	v_lshl_add_u64 v[230:231], s[30:31], 0, v[136:137]
	ds_read_b128 v[186:189], v152 offset:32768
	ds_read_b128 v[190:193], v152 offset:33792
	ds_read_b128 v[194:197], v152 offset:34816
	ds_read_b128 v[198:201], v152 offset:35840
	ds_read_b128 v[202:205], v152 offset:36864
	ds_read_b128 v[206:209], v152 offset:37888
	ds_read_b128 v[210:213], v152 offset:38912
	ds_read_b128 v[218:221], v152 offset:39936
	global_load_lds_dwordx4 v[230:231], off
	v_lshl_add_u64 v[230:231], s[30:31], 0, v[132:133]
	s_mov_b32 m0, s64
	s_nop 0
	global_load_lds_dwordx4 v[230:231], off
	s_waitcnt vmcnt(8)
	s_waitcnt lgkmcnt(0)
	s_barrier
	s_waitcnt lgkmcnt(0)
	v_mfma_f32_16x16x32_bf16 v[126:129], v[154:157], v[186:189], v[126:129]
	v_mfma_f32_16x16x32_bf16 v[122:125], v[162:165], v[186:189], v[122:125]
	v_mfma_f32_16x16x32_bf16 v[118:121], v[154:157], v[194:197], v[118:121]
	v_mfma_f32_16x16x32_bf16 v[114:117], v[162:165], v[194:197], v[114:117]
	v_mfma_f32_16x16x32_bf16 v[94:97], v[154:157], v[202:205], v[94:97]
	v_mfma_f32_16x16x32_bf16 v[90:93], v[162:165], v[202:205], v[90:93]
	v_mfma_f32_16x16x32_bf16 v[78:81], v[154:157], v[210:213], v[78:81]
	v_mfma_f32_16x16x32_bf16 v[74:77], v[162:165], v[210:213], v[74:77]
	v_mfma_f32_16x16x32_bf16 v[126:129], v[158:161], v[190:193], v[126:129]
	v_mfma_f32_16x16x32_bf16 v[122:125], v[166:169], v[190:193], v[122:125]
	v_mfma_f32_16x16x32_bf16 v[118:121], v[158:161], v[198:201], v[118:121]
	v_mfma_f32_16x16x32_bf16 v[114:117], v[166:169], v[198:201], v[114:117]
	v_mfma_f32_16x16x32_bf16 v[94:97], v[158:161], v[206:209], v[94:97]
	v_mfma_f32_16x16x32_bf16 v[90:93], v[166:169], v[206:209], v[90:93]
	v_mfma_f32_16x16x32_bf16 v[78:81], v[158:161], v[218:221], v[78:81]
	v_mfma_f32_16x16x32_bf16 v[74:77], v[166:169], v[218:221], v[74:77]
	v_mfma_f32_16x16x32_bf16 v[110:113], v[170:173], v[186:189], v[110:113]
	v_mfma_f32_16x16x32_bf16 v[106:109], v[178:181], v[186:189], v[106:109]
	v_mfma_f32_16x16x32_bf16 v[102:105], v[170:173], v[194:197], v[102:105]
	v_mfma_f32_16x16x32_bf16 v[98:101], v[178:181], v[194:197], v[98:101]
	v_mfma_f32_16x16x32_bf16 v[86:89], v[170:173], v[202:205], v[86:89]
	v_mfma_f32_16x16x32_bf16 v[82:85], v[178:181], v[202:205], v[82:85]
	v_mfma_f32_16x16x32_bf16 v[70:73], v[170:173], v[210:213], v[70:73]
	v_mfma_f32_16x16x32_bf16 v[66:69], v[178:181], v[210:213], v[66:69]
	v_mfma_f32_16x16x32_bf16 v[110:113], v[174:177], v[190:193], v[110:113]
	v_mfma_f32_16x16x32_bf16 v[106:109], v[182:185], v[190:193], v[106:109]
	v_mfma_f32_16x16x32_bf16 v[102:105], v[174:177], v[198:201], v[102:105]
	v_mfma_f32_16x16x32_bf16 v[98:101], v[182:185], v[198:201], v[98:101]
	v_mfma_f32_16x16x32_bf16 v[86:89], v[174:177], v[206:209], v[86:89]
	v_mfma_f32_16x16x32_bf16 v[82:85], v[182:185], v[206:209], v[82:85]
	v_mfma_f32_16x16x32_bf16 v[70:73], v[174:177], v[218:221], v[70:73]
	v_mfma_f32_16x16x32_bf16 v[66:69], v[182:185], v[218:221], v[66:69]
	s_barrier
	s_add_i32 s30, s80, s37
	v_lshl_add_u64 v[222:223], v[222:223], 0, s[16:17]
	s_mov_b32 m0, s30
	ds_read_b128 v[186:189], v152 offset:49152
	ds_read_b128 v[190:193], v152 offset:50176
	ds_read_b128 v[194:197], v152 offset:51200
	ds_read_b128 v[198:201], v152 offset:52224
	ds_read_b128 v[202:205], v152 offset:53248
	ds_read_b128 v[206:209], v152 offset:54272
	ds_read_b128 v[210:213], v152 offset:55296
	ds_read_b128 v[218:221], v152 offset:56320
	global_load_lds_dwordx4 v[222:223], off
	s_add_i32 m0, s30, 0x2000
	s_add_u32 s28, s28, 0x40080
	v_lshl_add_u64 v[222:223], v[224:225], 0, s[16:17]
	s_addc_u32 s29, s29, 0
	s_add_i32 s30, s81, s37
	global_load_lds_dwordx4 v[222:223], off
	v_lshl_add_u64 v[222:223], s[28:29], 0, v[134:135]
	s_mov_b32 m0, s30
	s_nop 0
	global_load_lds_dwordx4 v[222:223], off
	v_lshl_add_u64 v[222:223], s[28:29], 0, v[130:131]
	s_add_i32 m0, s30, 0x2000
	s_nop 0
	global_load_lds_dwordx4 v[222:223], off
	v_lshl_add_u64 v[222:223], v[226:227], 0, s[16:17]
	s_mov_b32 m0, s72
	s_nop 0
	global_load_lds_dwordx4 v[222:223], off
	v_lshl_add_u64 v[222:223], v[228:229], 0, s[16:17]
	s_mov_b32 m0, s73
	s_nop 0
	global_load_lds_dwordx4 v[222:223], off
	s_waitcnt vmcnt(8)
	s_waitcnt lgkmcnt(0)
	s_barrier
	s_waitcnt lgkmcnt(0)
	v_mfma_f32_16x16x32_bf16 v[62:65], v[154:157], v[186:189], v[62:65]
	v_mfma_f32_16x16x32_bf16 v[58:61], v[162:165], v[186:189], v[58:61]
	v_mfma_f32_16x16x32_bf16 v[50:53], v[154:157], v[194:197], v[50:53]
	v_mfma_f32_16x16x32_bf16 v[42:45], v[162:165], v[194:197], v[42:45]
	v_mfma_f32_16x16x32_bf16 v[30:33], v[154:157], v[202:205], v[30:33]
	v_mfma_f32_16x16x32_bf16 v[26:29], v[162:165], v[202:205], v[26:29]
	v_mfma_f32_16x16x32_bf16 v[22:25], v[154:157], v[210:213], v[22:25]
	v_mfma_f32_16x16x32_bf16 v[18:21], v[162:165], v[210:213], v[18:21]
	v_mfma_f32_16x16x32_bf16 v[62:65], v[158:161], v[190:193], v[62:65]
	v_mfma_f32_16x16x32_bf16 v[58:61], v[166:169], v[190:193], v[58:61]
	v_mfma_f32_16x16x32_bf16 v[50:53], v[158:161], v[198:201], v[50:53]
	v_mfma_f32_16x16x32_bf16 v[42:45], v[166:169], v[198:201], v[42:45]
	v_mfma_f32_16x16x32_bf16 v[30:33], v[158:161], v[206:209], v[30:33]
	v_mfma_f32_16x16x32_bf16 v[26:29], v[166:169], v[206:209], v[26:29]
	v_mfma_f32_16x16x32_bf16 v[22:25], v[158:161], v[218:221], v[22:25]
	v_mfma_f32_16x16x32_bf16 v[18:21], v[166:169], v[218:221], v[18:21]
	v_mfma_f32_16x16x32_bf16 v[54:57], v[170:173], v[186:189], v[54:57]
	v_mfma_f32_16x16x32_bf16 v[46:49], v[178:181], v[186:189], v[46:49]
	v_mfma_f32_16x16x32_bf16 v[38:41], v[170:173], v[194:197], v[38:41]
	v_mfma_f32_16x16x32_bf16 v[34:37], v[178:181], v[194:197], v[34:37]
	v_mfma_f32_16x16x32_bf16 v[14:17], v[170:173], v[202:205], v[14:17]
	v_mfma_f32_16x16x32_bf16 v[10:13], v[178:181], v[202:205], v[10:13]
	v_mfma_f32_16x16x32_bf16 v[6:9], v[170:173], v[210:213], v[6:9]
	v_mfma_f32_16x16x32_bf16 v[2:5], v[178:181], v[210:213], v[2:5]
	v_mfma_f32_16x16x32_bf16 v[54:57], v[174:177], v[190:193], v[54:57]
	v_mfma_f32_16x16x32_bf16 v[46:49], v[182:185], v[190:193], v[46:49]
	v_mfma_f32_16x16x32_bf16 v[38:41], v[174:177], v[198:201], v[38:41]
	v_mfma_f32_16x16x32_bf16 v[34:37], v[182:185], v[198:201], v[34:37]
	v_mfma_f32_16x16x32_bf16 v[14:17], v[174:177], v[206:209], v[14:17]
	v_mfma_f32_16x16x32_bf16 v[10:13], v[182:185], v[206:209], v[10:13]
	v_mfma_f32_16x16x32_bf16 v[6:9], v[174:177], v[218:221], v[6:9]
	v_mfma_f32_16x16x32_bf16 v[2:5], v[182:185], v[218:221], v[2:5]
	s_barrier
	s_add_i32 s79, s79, 2
	s_add_u32 s26, s26, 0x100
	s_addc_u32 s27, s27, 0
	s_cmp_gt_u32 s79, 13
	s_cbranch_scc0 .LBB0_451
	s_add_u32 s4, s4, 0xffffff00
	s_addc_u32 s5, s5, -1
	s_andn2_b64 vcc, exec, s[8:9]
	s_cbranch_vccnz .LBB0_446
	v_mov_b32_e32 v2, 0
	s_mov_b32 s2, s18
	s_mov_b32 s86, s20
	s_mov_b64 s[10:11], s[24:25]
	s_mov_b32 s65, s76
	v_mov_b32_e32 v3, v2
	v_mov_b32_e32 v4, v2
	v_mov_b32_e32 v5, v2
	v_mov_b32_e32 v6, v2
	v_mov_b32_e32 v7, v2
	v_mov_b32_e32 v8, v2
	v_mov_b32_e32 v9, v2
	v_mov_b32_e32 v10, v2
	v_mov_b32_e32 v11, v2
	v_mov_b32_e32 v12, v2
	v_mov_b32_e32 v13, v2
	v_mov_b32_e32 v14, v2
	v_mov_b32_e32 v15, v2
	v_mov_b32_e32 v16, v2
	v_mov_b32_e32 v17, v2
	v_mov_b32_e32 v34, v2
	v_mov_b32_e32 v35, v2
	v_mov_b32_e32 v36, v2
	v_mov_b32_e32 v37, v2
	v_mov_b32_e32 v38, v2
	v_mov_b32_e32 v39, v2
	v_mov_b32_e32 v40, v2
	v_mov_b32_e32 v41, v2
	v_mov_b32_e32 v46, v2
	v_mov_b32_e32 v47, v2
	v_mov_b32_e32 v48, v2
	v_mov_b32_e32 v49, v2
	v_mov_b32_e32 v54, v2
	v_mov_b32_e32 v55, v2
	v_mov_b32_e32 v56, v2
	v_mov_b32_e32 v57, v2
	v_mov_b32_e32 v18, v2
	v_mov_b32_e32 v19, v2
	v_mov_b32_e32 v20, v2
	v_mov_b32_e32 v21, v2
	v_mov_b32_e32 v22, v2
	v_mov_b32_e32 v23, v2
	v_mov_b32_e32 v24, v2
	v_mov_b32_e32 v25, v2
	v_mov_b32_e32 v26, v2
	v_mov_b32_e32 v27, v2
	v_mov_b32_e32 v28, v2
	v_mov_b32_e32 v29, v2
	v_mov_b32_e32 v30, v2
	v_mov_b32_e32 v31, v2
	v_mov_b32_e32 v32, v2
	v_mov_b32_e32 v33, v2
	v_mov_b32_e32 v42, v2
	v_mov_b32_e32 v43, v2
	v_mov_b32_e32 v44, v2
	v_mov_b32_e32 v45, v2
	v_mov_b32_e32 v50, v2
	v_mov_b32_e32 v51, v2
	v_mov_b32_e32 v52, v2
	v_mov_b32_e32 v53, v2
	v_mov_b32_e32 v58, v2
	v_mov_b32_e32 v59, v2
	v_mov_b32_e32 v60, v2
	v_mov_b32_e32 v61, v2
	v_mov_b32_e32 v62, v2
	v_mov_b32_e32 v63, v2
	v_mov_b32_e32 v64, v2
	v_mov_b32_e32 v65, v2
	v_mov_b32_e32 v66, v2
	v_mov_b32_e32 v67, v2
	v_mov_b32_e32 v68, v2
	v_mov_b32_e32 v69, v2
	v_mov_b32_e32 v70, v2
	v_mov_b32_e32 v71, v2
	v_mov_b32_e32 v72, v2
	v_mov_b32_e32 v73, v2
	v_mov_b32_e32 v82, v2
	v_mov_b32_e32 v83, v2
	v_mov_b32_e32 v84, v2
	v_mov_b32_e32 v85, v2
	v_mov_b32_e32 v86, v2
	v_mov_b32_e32 v87, v2
	v_mov_b32_e32 v88, v2
	v_mov_b32_e32 v89, v2
	v_mov_b32_e32 v98, v2
	v_mov_b32_e32 v99, v2
	v_mov_b32_e32 v100, v2
	v_mov_b32_e32 v101, v2
	v_mov_b32_e32 v102, v2
	v_mov_b32_e32 v103, v2
	v_mov_b32_e32 v104, v2
	v_mov_b32_e32 v105, v2
	v_mov_b32_e32 v106, v2
	v_mov_b32_e32 v107, v2
	v_mov_b32_e32 v108, v2
	v_mov_b32_e32 v109, v2
	v_mov_b32_e32 v110, v2
	v_mov_b32_e32 v111, v2
	v_mov_b32_e32 v112, v2
	v_mov_b32_e32 v113, v2
	v_mov_b32_e32 v74, v2
	v_mov_b32_e32 v75, v2
	v_mov_b32_e32 v76, v2
	v_mov_b32_e32 v77, v2
	v_mov_b32_e32 v78, v2
	v_mov_b32_e32 v79, v2
	v_mov_b32_e32 v80, v2
	v_mov_b32_e32 v81, v2
	v_mov_b32_e32 v90, v2
	v_mov_b32_e32 v91, v2
	v_mov_b32_e32 v92, v2
	v_mov_b32_e32 v93, v2
	v_mov_b32_e32 v94, v2
	v_mov_b32_e32 v95, v2
	v_mov_b32_e32 v96, v2
	v_mov_b32_e32 v97, v2
	v_mov_b32_e32 v114, v2
	v_mov_b32_e32 v115, v2
	v_mov_b32_e32 v116, v2
	v_mov_b32_e32 v117, v2
	v_mov_b32_e32 v118, v2
	v_mov_b32_e32 v119, v2
	v_mov_b32_e32 v120, v2
	v_mov_b32_e32 v121, v2
	v_mov_b32_e32 v122, v2
	v_mov_b32_e32 v123, v2
	v_mov_b32_e32 v124, v2
	v_mov_b32_e32 v125, v2
	v_mov_b32_e32 v126, v2
	v_mov_b32_e32 v127, v2
	v_mov_b32_e32 v128, v2
	v_mov_b32_e32 v129, v2
	s_andn2_b64 vcc, exec, s[6:7]
	s_cbranch_vccnz .LBB0_447

.LBB0_581:
	ds_read_b128 v[130:133], v168
	ds_read_b128 v[134:137], v168 offset:1024
	ds_read_b128 v[138:141], v168 offset:2048
	ds_read_b128 v[142:145], v168 offset:3072
	ds_read_b128 v[162:165], v169
	ds_read_b128 v[172:175], v169 offset:1024
	ds_read_b128 v[176:179], v169 offset:2048
	ds_read_b128 v[180:183], v169 offset:3072
	s_add_u32 s56, s44, 0xfffc0080
	s_addc_u32 s57, s45, -1
	s_cmp_eq_u32 s80, 12
	s_cselect_b32 s59, s4, s57
	s_cselect_b32 s58, s5, s56
	s_cselect_b32 s57, s29, s79
	s_cselect_b32 s56, s31, s78
	v_lshl_add_u64 v[216:217], s[44:45], 0, v[154:155]
	s_add_i32 m0, s41, 0xc000
	ds_read_b128 v[184:187], v170
	ds_read_b128 v[188:191], v170 offset:1024
	ds_read_b128 v[192:195], v170 offset:2048
	ds_read_b128 v[196:199], v170 offset:3072
	ds_read_b128 v[200:203], v170 offset:4096
	ds_read_b128 v[204:207], v170 offset:5120
	ds_read_b128 v[208:211], v170 offset:6144
	ds_read_b128 v[212:215], v170 offset:7168
	global_load_lds_dwordx4 v[216:217], off
	v_lshl_add_u64 v[216:217], s[44:45], 0, v[156:157]
	s_add_i32 m0, s41, 0xe000
	s_nop 0
	global_load_lds_dwordx4 v[216:217], off
	s_waitcnt vmcnt(8)
	s_waitcnt lgkmcnt(0)
	s_barrier
	s_waitcnt lgkmcnt(0)
	v_mfma_f32_16x16x32_bf16 v[126:129], v[130:133], v[184:187], v[126:129]
	v_mfma_f32_16x16x32_bf16 v[122:125], v[138:141], v[184:187], v[122:125]
	v_mfma_f32_16x16x32_bf16 v[118:121], v[130:133], v[192:195], v[118:121]
	v_mfma_f32_16x16x32_bf16 v[114:117], v[138:141], v[192:195], v[114:117]
	v_mfma_f32_16x16x32_bf16 v[94:97], v[130:133], v[200:203], v[94:97]
	v_mfma_f32_16x16x32_bf16 v[90:93], v[138:141], v[200:203], v[90:93]
	v_mfma_f32_16x16x32_bf16 v[78:81], v[130:133], v[208:211], v[78:81]
	v_mfma_f32_16x16x32_bf16 v[74:77], v[138:141], v[208:211], v[74:77]
	v_mfma_f32_16x16x32_bf16 v[126:129], v[134:137], v[188:191], v[126:129]
	v_mfma_f32_16x16x32_bf16 v[122:125], v[142:145], v[188:191], v[122:125]
	v_mfma_f32_16x16x32_bf16 v[118:121], v[134:137], v[196:199], v[118:121]
	v_mfma_f32_16x16x32_bf16 v[114:117], v[142:145], v[196:199], v[114:117]
	v_mfma_f32_16x16x32_bf16 v[94:97], v[134:137], v[204:207], v[94:97]
	v_mfma_f32_16x16x32_bf16 v[90:93], v[142:145], v[204:207], v[90:93]
	v_mfma_f32_16x16x32_bf16 v[78:81], v[134:137], v[212:215], v[78:81]
	v_mfma_f32_16x16x32_bf16 v[74:77], v[142:145], v[212:215], v[74:77]
	v_mfma_f32_16x16x32_bf16 v[110:113], v[162:165], v[184:187], v[110:113]
	v_mfma_f32_16x16x32_bf16 v[106:109], v[176:179], v[184:187], v[106:109]
	v_mfma_f32_16x16x32_bf16 v[102:105], v[162:165], v[192:195], v[102:105]
	v_mfma_f32_16x16x32_bf16 v[98:101], v[176:179], v[192:195], v[98:101]
	v_mfma_f32_16x16x32_bf16 v[86:89], v[162:165], v[200:203], v[86:89]
	v_mfma_f32_16x16x32_bf16 v[82:85], v[176:179], v[200:203], v[82:85]
	v_mfma_f32_16x16x32_bf16 v[70:73], v[162:165], v[208:211], v[70:73]
	v_mfma_f32_16x16x32_bf16 v[66:69], v[176:179], v[208:211], v[66:69]
	v_mfma_f32_16x16x32_bf16 v[110:113], v[172:175], v[188:191], v[110:113]
	v_mfma_f32_16x16x32_bf16 v[106:109], v[180:183], v[188:191], v[106:109]
	v_mfma_f32_16x16x32_bf16 v[102:105], v[172:175], v[196:199], v[102:105]
	v_mfma_f32_16x16x32_bf16 v[98:101], v[180:183], v[196:199], v[98:101]
	v_mfma_f32_16x16x32_bf16 v[86:89], v[172:175], v[204:207], v[86:89]
	v_mfma_f32_16x16x32_bf16 v[82:85], v[180:183], v[204:207], v[82:85]
	v_mfma_f32_16x16x32_bf16 v[70:73], v[172:175], v[212:215], v[70:73]
	v_mfma_f32_16x16x32_bf16 v[66:69], v[180:183], v[212:215], v[66:69]
	s_barrier
	s_add_i32 s81, s71, s3
	v_lshl_add_u64 v[216:217], s[56:57], 0, v[150:151]
	s_mov_b32 m0, s81
	ds_read_b128 v[184:187], v170 offset:16384
	ds_read_b128 v[188:191], v170 offset:17408
	ds_read_b128 v[192:195], v170 offset:18432
	ds_read_b128 v[196:199], v170 offset:19456
	ds_read_b128 v[200:203], v170 offset:20480
	ds_read_b128 v[204:207], v170 offset:21504
	ds_read_b128 v[208:211], v170 offset:22528
	ds_read_b128 v[212:215], v170 offset:23552
	global_load_lds_dwordx4 v[216:217], off
	s_add_i32 m0, s81, 0x2000
	s_add_u32 s82, s56, 0x40000
	v_lshl_add_u64 v[218:219], s[56:57], 0, v[146:147]
	s_addc_u32 s83, s57, 0
	s_add_i32 s81, s72, s3
	global_load_lds_dwordx4 v[218:219], off
	v_lshl_add_u64 v[220:221], s[82:83], 0, v[150:151]
	s_mov_b32 m0, s81
	v_lshl_add_u64 v[222:223], s[58:59], 0, v[148:149]
	global_load_lds_dwordx4 v[220:221], off
	v_lshl_add_u64 v[220:221], s[82:83], 0, v[146:147]
	s_add_i32 m0, s81, 0x2000
	s_nop 0
	global_load_lds_dwordx4 v[220:221], off
	v_lshl_add_u64 v[220:221], s[58:59], 0, v[152:153]
	s_mov_b32 m0, s41
	s_nop 0
	global_load_lds_dwordx4 v[220:221], off
	s_mov_b32 m0, s60
	s_nop 0
	global_load_lds_dwordx4 v[222:223], off
	s_waitcnt vmcnt(8)
	s_waitcnt lgkmcnt(0)
	s_barrier
	s_waitcnt lgkmcnt(0)
	v_mfma_f32_16x16x32_bf16 v[62:65], v[130:133], v[184:187], v[62:65]
	v_mfma_f32_16x16x32_bf16 v[58:61], v[138:141], v[184:187], v[58:61]
	v_mfma_f32_16x16x32_bf16 v[46:49], v[130:133], v[192:195], v[46:49]
	v_mfma_f32_16x16x32_bf16 v[42:45], v[138:141], v[192:195], v[42:45]
	v_mfma_f32_16x16x32_bf16 v[30:33], v[130:133], v[200:203], v[30:33]
	v_mfma_f32_16x16x32_bf16 v[26:29], v[138:141], v[200:203], v[26:29]
	v_mfma_f32_16x16x32_bf16 v[14:17], v[130:133], v[208:211], v[14:17]
	v_mfma_f32_16x16x32_bf16 v[10:13], v[138:141], v[208:211], v[10:13]
	v_mfma_f32_16x16x32_bf16 v[62:65], v[134:137], v[188:191], v[62:65]
	v_mfma_f32_16x16x32_bf16 v[58:61], v[142:145], v[188:191], v[58:61]
	v_mfma_f32_16x16x32_bf16 v[46:49], v[134:137], v[196:199], v[46:49]
	v_mfma_f32_16x16x32_bf16 v[42:45], v[142:145], v[196:199], v[42:45]
	v_mfma_f32_16x16x32_bf16 v[30:33], v[134:137], v[204:207], v[30:33]
	v_mfma_f32_16x16x32_bf16 v[26:29], v[142:145], v[204:207], v[26:29]
	v_mfma_f32_16x16x32_bf16 v[14:17], v[134:137], v[212:215], v[14:17]
	v_mfma_f32_16x16x32_bf16 v[10:13], v[142:145], v[212:215], v[10:13]
	v_mfma_f32_16x16x32_bf16 v[54:57], v[162:165], v[184:187], v[54:57]
	v_mfma_f32_16x16x32_bf16 v[50:53], v[176:179], v[184:187], v[50:53]
	v_mfma_f32_16x16x32_bf16 v[38:41], v[162:165], v[192:195], v[38:41]
	v_mfma_f32_16x16x32_bf16 v[34:37], v[176:179], v[192:195], v[34:37]
	v_mfma_f32_16x16x32_bf16 v[22:25], v[162:165], v[200:203], v[22:25]
	v_mfma_f32_16x16x32_bf16 v[18:21], v[176:179], v[200:203], v[18:21]
	v_mfma_f32_16x16x32_bf16 v[6:9], v[162:165], v[208:211], v[6:9]
	v_mfma_f32_16x16x32_bf16 v[2:5], v[176:179], v[208:211], v[2:5]
	v_mfma_f32_16x16x32_bf16 v[54:57], v[172:175], v[188:191], v[54:57]
	v_mfma_f32_16x16x32_bf16 v[50:53], v[180:183], v[188:191], v[50:53]
	v_mfma_f32_16x16x32_bf16 v[38:41], v[172:175], v[196:199], v[38:41]
	v_mfma_f32_16x16x32_bf16 v[34:37], v[180:183], v[196:199], v[34:37]
	v_mfma_f32_16x16x32_bf16 v[22:25], v[172:175], v[204:207], v[22:25]
	v_mfma_f32_16x16x32_bf16 v[18:21], v[180:183], v[204:207], v[18:21]
	v_mfma_f32_16x16x32_bf16 v[6:9], v[172:175], v[212:215], v[6:9]
	v_mfma_f32_16x16x32_bf16 v[2:5], v[180:183], v[212:215], v[2:5]
	s_barrier
	s_add_i32 s81, 0, 0x18000
	s_add_i32 s82, 0, 0x1c000
	v_add_u32_e32 v142, s81, v166
	v_add_u32_e32 v171, s82, v166
	ds_read_b128 v[130:133], v142
	ds_read_b128 v[134:137], v142 offset:1024
	ds_read_b128 v[138:141], v142 offset:2048
	ds_read_b128 v[142:145], v142 offset:3072
	ds_read_b128 v[162:165], v171
	ds_read_b128 v[172:175], v171 offset:1024
	ds_read_b128 v[176:179], v171 offset:2048
	ds_read_b128 v[180:183], v171 offset:3072
	s_add_u32 s58, s58, 0x40000
	s_addc_u32 s59, s59, 0
	s_mov_b32 m0, s61
	v_lshl_add_u64 v[224:225], s[58:59], 0, v[152:153]
	ds_read_b128 v[184:187], v170 offset:32768
	ds_read_b128 v[188:191], v170 offset:33792
	ds_read_b128 v[192:195], v170 offset:34816
	ds_read_b128 v[196:199], v170 offset:35840
	ds_read_b128 v[200:203], v170 offset:36864
	ds_read_b128 v[204:207], v170 offset:37888
	ds_read_b128 v[208:211], v170 offset:38912
	ds_read_b128 v[212:215], v170 offset:39936
	global_load_lds_dwordx4 v[224:225], off
	v_lshl_add_u64 v[224:225], s[58:59], 0, v[148:149]
	s_mov_b32 m0, s62
	s_nop 0
	global_load_lds_dwordx4 v[224:225], off
	s_waitcnt vmcnt(8)
	s_waitcnt lgkmcnt(0)
	s_barrier
	s_waitcnt lgkmcnt(0)
	v_mfma_f32_16x16x32_bf16 v[126:129], v[130:133], v[184:187], v[126:129]
	v_mfma_f32_16x16x32_bf16 v[122:125], v[138:141], v[184:187], v[122:125]
	v_mfma_f32_16x16x32_bf16 v[118:121], v[130:133], v[192:195], v[118:121]
	v_mfma_f32_16x16x32_bf16 v[114:117], v[138:141], v[192:195], v[114:117]
	v_mfma_f32_16x16x32_bf16 v[94:97], v[130:133], v[200:203], v[94:97]
	v_mfma_f32_16x16x32_bf16 v[90:93], v[138:141], v[200:203], v[90:93]
	v_mfma_f32_16x16x32_bf16 v[78:81], v[130:133], v[208:211], v[78:81]
	v_mfma_f32_16x16x32_bf16 v[74:77], v[138:141], v[208:211], v[74:77]
	v_mfma_f32_16x16x32_bf16 v[126:129], v[134:137], v[188:191], v[126:129]
	v_mfma_f32_16x16x32_bf16 v[122:125], v[142:145], v[188:191], v[122:125]
	v_mfma_f32_16x16x32_bf16 v[118:121], v[134:137], v[196:199], v[118:121]
	v_mfma_f32_16x16x32_bf16 v[114:117], v[142:145], v[196:199], v[114:117]
	v_mfma_f32_16x16x32_bf16 v[94:97], v[134:137], v[204:207], v[94:97]
	v_mfma_f32_16x16x32_bf16 v[90:93], v[142:145], v[204:207], v[90:93]
	v_mfma_f32_16x16x32_bf16 v[78:81], v[134:137], v[212:215], v[78:81]
	v_mfma_f32_16x16x32_bf16 v[74:77], v[142:145], v[212:215], v[74:77]
	v_mfma_f32_16x16x32_bf16 v[110:113], v[162:165], v[184:187], v[110:113]
	v_mfma_f32_16x16x32_bf16 v[106:109], v[176:179], v[184:187], v[106:109]
	v_mfma_f32_16x16x32_bf16 v[102:105], v[162:165], v[192:195], v[102:105]
	v_mfma_f32_16x16x32_bf16 v[98:101], v[176:179], v[192:195], v[98:101]
	v_mfma_f32_16x16x32_bf16 v[86:89], v[162:165], v[200:203], v[86:89]
	v_mfma_f32_16x16x32_bf16 v[82:85], v[176:179], v[200:203], v[82:85]
	v_mfma_f32_16x16x32_bf16 v[70:73], v[162:165], v[208:211], v[70:73]
	v_mfma_f32_16x16x32_bf16 v[66:69], v[176:179], v[208:211], v[66:69]
	v_mfma_f32_16x16x32_bf16 v[110:113], v[172:175], v[188:191], v[110:113]
	v_mfma_f32_16x16x32_bf16 v[106:109], v[180:183], v[188:191], v[106:109]
	v_mfma_f32_16x16x32_bf16 v[102:105], v[172:175], v[196:199], v[102:105]
	v_mfma_f32_16x16x32_bf16 v[98:101], v[180:183], v[196:199], v[98:101]
	v_mfma_f32_16x16x32_bf16 v[86:89], v[172:175], v[204:207], v[86:89]
	v_mfma_f32_16x16x32_bf16 v[82:85], v[180:183], v[204:207], v[82:85]
	v_mfma_f32_16x16x32_bf16 v[70:73], v[172:175], v[212:215], v[70:73]
	v_mfma_f32_16x16x32_bf16 v[66:69], v[180:183], v[212:215], v[66:69]
	s_barrier
	s_add_i32 s58, s81, s3
	v_lshl_add_u64 v[216:217], v[216:217], 0, s[16:17]
	s_mov_b32 m0, s58
	ds_read_b128 v[184:187], v170 offset:49152
	ds_read_b128 v[188:191], v170 offset:50176
	ds_read_b128 v[192:195], v170 offset:51200
	ds_read_b128 v[196:199], v170 offset:52224
	ds_read_b128 v[200:203], v170 offset:53248
	ds_read_b128 v[204:207], v170 offset:54272
	ds_read_b128 v[208:211], v170 offset:55296
	ds_read_b128 v[212:215], v170 offset:56320
	global_load_lds_dwordx4 v[216:217], off
	s_add_i32 m0, s58, 0x2000
	s_add_u32 s56, s56, 0x40080
	v_lshl_add_u64 v[216:217], v[218:219], 0, s[16:17]
	s_addc_u32 s57, s57, 0
	s_add_i32 s58, s82, s3
	global_load_lds_dwordx4 v[216:217], off
	v_lshl_add_u64 v[216:217], s[56:57], 0, v[150:151]
	s_mov_b32 m0, s58
	s_nop 0
	global_load_lds_dwordx4 v[216:217], off
	v_lshl_add_u64 v[216:217], s[56:57], 0, v[146:147]
	s_add_i32 m0, s58, 0x2000
	s_nop 0
	global_load_lds_dwordx4 v[216:217], off
	v_lshl_add_u64 v[216:217], v[220:221], 0, s[16:17]
	s_mov_b32 m0, s64
	s_nop 0
	global_load_lds_dwordx4 v[216:217], off
	v_lshl_add_u64 v[216:217], v[222:223], 0, s[16:17]
	s_mov_b32 m0, s65
	s_nop 0
	global_load_lds_dwordx4 v[216:217], off
	s_waitcnt vmcnt(8)
	s_waitcnt lgkmcnt(0)
	s_barrier
	s_waitcnt lgkmcnt(0)
	v_mfma_f32_16x16x32_bf16 v[62:65], v[130:133], v[184:187], v[62:65]
	v_mfma_f32_16x16x32_bf16 v[58:61], v[138:141], v[184:187], v[58:61]
	v_mfma_f32_16x16x32_bf16 v[46:49], v[130:133], v[192:195], v[46:49]
	v_mfma_f32_16x16x32_bf16 v[42:45], v[138:141], v[192:195], v[42:45]
	v_mfma_f32_16x16x32_bf16 v[30:33], v[130:133], v[200:203], v[30:33]
	v_mfma_f32_16x16x32_bf16 v[26:29], v[138:141], v[200:203], v[26:29]
	v_mfma_f32_16x16x32_bf16 v[14:17], v[130:133], v[208:211], v[14:17]
	v_mfma_f32_16x16x32_bf16 v[10:13], v[138:141], v[208:211], v[10:13]
	v_mfma_f32_16x16x32_bf16 v[62:65], v[134:137], v[188:191], v[62:65]
	v_mfma_f32_16x16x32_bf16 v[58:61], v[142:145], v[188:191], v[58:61]
	v_mfma_f32_16x16x32_bf16 v[46:49], v[134:137], v[196:199], v[46:49]
	v_mfma_f32_16x16x32_bf16 v[42:45], v[142:145], v[196:199], v[42:45]
	v_mfma_f32_16x16x32_bf16 v[30:33], v[134:137], v[204:207], v[30:33]
	v_mfma_f32_16x16x32_bf16 v[26:29], v[142:145], v[204:207], v[26:29]
	v_mfma_f32_16x16x32_bf16 v[14:17], v[134:137], v[212:215], v[14:17]
	v_mfma_f32_16x16x32_bf16 v[10:13], v[142:145], v[212:215], v[10:13]
	v_mfma_f32_16x16x32_bf16 v[54:57], v[162:165], v[184:187], v[54:57]
	v_mfma_f32_16x16x32_bf16 v[50:53], v[176:179], v[184:187], v[50:53]
	v_mfma_f32_16x16x32_bf16 v[38:41], v[162:165], v[192:195], v[38:41]
	v_mfma_f32_16x16x32_bf16 v[34:37], v[176:179], v[192:195], v[34:37]
	v_mfma_f32_16x16x32_bf16 v[22:25], v[162:165], v[200:203], v[22:25]
	v_mfma_f32_16x16x32_bf16 v[18:21], v[176:179], v[200:203], v[18:21]
	v_mfma_f32_16x16x32_bf16 v[6:9], v[162:165], v[208:211], v[6:9]
	v_mfma_f32_16x16x32_bf16 v[2:5], v[176:179], v[208:211], v[2:5]
	v_mfma_f32_16x16x32_bf16 v[54:57], v[172:175], v[188:191], v[54:57]
	v_mfma_f32_16x16x32_bf16 v[50:53], v[180:183], v[188:191], v[50:53]
	v_mfma_f32_16x16x32_bf16 v[38:41], v[172:175], v[196:199], v[38:41]
	v_mfma_f32_16x16x32_bf16 v[34:37], v[180:183], v[196:199], v[34:37]
	v_mfma_f32_16x16x32_bf16 v[22:25], v[172:175], v[204:207], v[22:25]
	v_mfma_f32_16x16x32_bf16 v[18:21], v[180:183], v[204:207], v[18:21]
	v_mfma_f32_16x16x32_bf16 v[6:9], v[172:175], v[212:215], v[6:9]
	v_mfma_f32_16x16x32_bf16 v[2:5], v[180:183], v[212:215], v[2:5]
	s_barrier
	s_add_i32 s80, s80, 2
	s_add_u32 s44, s44, 0x100
	s_addc_u32 s45, s45, 0
	s_add_u32 s78, s78, 0x100
	s_addc_u32 s79, s79, 0
	s_cmp_gt_u32 s80, 13
	s_cbranch_scc0 .LBB0_581
	s_and_b64 vcc, exec, s[18:19]
	s_cbranch_vccz .LBB0_584
	s_barrier

.LBB0_649:
	v_add_u32_e32 v164, s57, v150
	v_add_u32_e32 v173, s58, v150
	s_add_u32 s28, s14, s26
	ds_read_b128 v[152:155], v164
	ds_read_b128 v[156:159], v164 offset:1024
	ds_read_b128 v[160:163], v164 offset:2048
	ds_read_b128 v[164:167], v164 offset:3072
	ds_read_b128 v[168:171], v173
	ds_read_b128 v[174:177], v173 offset:1024
	ds_read_b128 v[178:181], v173 offset:2048
	ds_read_b128 v[182:185], v173 offset:3072
	s_addc_u32 s29, s15, s27
	s_add_u32 s28, s28, 0x100
	s_addc_u32 s29, s29, 0
	s_add_u32 s65, s60, s26
	s_addc_u32 s66, s61, s27
	s_cmpk_eq_i32 s26, 0x1f00
	s_cselect_b32 s31, s21, s29
	s_cselect_b32 s30, s62, s28
	s_cselect_b32 s29, s19, s66
	s_cselect_b32 s28, s63, s65
	v_lshl_add_u64 v[218:219], v[146:147], 0, s[26:27]
	s_add_i32 m0, s37, 0xc000
	ds_read_b128 v[186:189], v151
	ds_read_b128 v[190:193], v151 offset:1024
	ds_read_b128 v[194:197], v151 offset:2048
	ds_read_b128 v[198:201], v151 offset:3072
	ds_read_b128 v[202:205], v151 offset:4096
	ds_read_b128 v[206:209], v151 offset:5120
	global_load_lds_dwordx4 v[218:219], off
	v_lshl_add_u64 v[218:219], v[148:149], 0, s[26:27]
	s_add_i32 m0, s37, 0xe000
	s_nop 0
	global_load_lds_dwordx4 v[218:219], off
	s_waitcnt vmcnt(8)
	s_waitcnt lgkmcnt(0)
	s_barrier
	s_waitcnt lgkmcnt(0)
	v_mfma_f32_16x16x32_bf16 v[114:117], v[152:155], v[186:189], v[114:117]
	v_mfma_f32_16x16x32_bf16 v[106:109], v[160:163], v[186:189], v[106:109]
	v_mfma_f32_16x16x32_bf16 v[130:133], v[152:155], v[194:197], v[130:133]
	v_mfma_f32_16x16x32_bf16 v[78:81], v[160:163], v[194:197], v[78:81]
	v_mfma_f32_16x16x32_bf16 v[126:129], v[152:155], v[202:205], v[126:129]
	v_mfma_f32_16x16x32_bf16 v[118:121], v[160:163], v[202:205], v[118:121]
	v_mfma_f32_16x16x32_bf16 v[114:117], v[156:159], v[190:193], v[114:117]
	v_mfma_f32_16x16x32_bf16 v[106:109], v[164:167], v[190:193], v[106:109]
	v_mfma_f32_16x16x32_bf16 v[130:133], v[156:159], v[198:201], v[130:133]
	v_mfma_f32_16x16x32_bf16 v[78:81], v[164:167], v[198:201], v[78:81]
	v_mfma_f32_16x16x32_bf16 v[126:129], v[156:159], v[206:209], v[126:129]
	v_mfma_f32_16x16x32_bf16 v[118:121], v[164:167], v[206:209], v[118:121]
	v_mfma_f32_16x16x32_bf16 v[98:101], v[168:171], v[186:189], v[98:101]
	v_mfma_f32_16x16x32_bf16 v[82:85], v[178:181], v[186:189], v[82:85]
	v_mfma_f32_16x16x32_bf16 v[86:89], v[168:171], v[194:197], v[86:89]
	v_mfma_f32_16x16x32_bf16 v[90:93], v[178:181], v[194:197], v[90:93]
	v_mfma_f32_16x16x32_bf16 v[110:113], v[168:171], v[202:205], v[110:113]
	v_mfma_f32_16x16x32_bf16 v[94:97], v[178:181], v[202:205], v[94:97]
	v_mfma_f32_16x16x32_bf16 v[98:101], v[174:177], v[190:193], v[98:101]
	v_mfma_f32_16x16x32_bf16 v[82:85], v[182:185], v[190:193], v[82:85]
	v_mfma_f32_16x16x32_bf16 v[86:89], v[174:177], v[198:201], v[86:89]
	v_mfma_f32_16x16x32_bf16 v[90:93], v[182:185], v[198:201], v[90:93]
	v_mfma_f32_16x16x32_bf16 v[110:113], v[174:177], v[206:209], v[110:113]
	v_mfma_f32_16x16x32_bf16 v[94:97], v[182:185], v[206:209], v[94:97]
	s_barrier
	s_add_i32 s65, s57, s35
	v_lshl_add_u64 v[218:219], s[28:29], 0, v[134:135]
	s_mov_b32 m0, s65
	ds_read_b128 v[186:189], v151 offset:16384
	ds_read_b128 v[190:193], v151 offset:17408
	ds_read_b128 v[194:197], v151 offset:18432
	ds_read_b128 v[198:201], v151 offset:19456
	ds_read_b128 v[202:205], v151 offset:20480
	ds_read_b128 v[206:209], v151 offset:21504
	global_load_lds_dwordx4 v[218:219], off
	s_add_i32 m0, s65, 0x2000
	s_add_u32 s66, s28, 0x100000
	v_lshl_add_u64 v[220:221], s[28:29], 0, v[122:123]
	s_addc_u32 s67, s29, 0
	s_add_i32 s65, s58, s35
	global_load_lds_dwordx4 v[220:221], off
	v_lshl_add_u64 v[222:223], s[66:67], 0, v[134:135]
	s_mov_b32 m0, s65
	v_lshl_add_u64 v[224:225], s[30:31], 0, v[124:125]
	global_load_lds_dwordx4 v[222:223], off
	v_lshl_add_u64 v[222:223], s[66:67], 0, v[122:123]
	s_add_i32 m0, s65, 0x2000
	s_nop 0
	global_load_lds_dwordx4 v[222:223], off
	v_lshl_add_u64 v[222:223], s[30:31], 0, v[136:137]
	s_mov_b32 m0, s37
	s_nop 0
	global_load_lds_dwordx4 v[222:223], off
	s_mov_b32 m0, s41
	s_nop 0
	global_load_lds_dwordx4 v[224:225], off
	s_waitcnt vmcnt(8)
	s_waitcnt lgkmcnt(0)
	s_barrier
	s_waitcnt lgkmcnt(0)
	v_mfma_f32_16x16x32_bf16 v[62:65], v[152:155], v[186:189], v[62:65]
	v_mfma_f32_16x16x32_bf16 v[58:61], v[160:163], v[186:189], v[58:61]
	v_mfma_f32_16x16x32_bf16 v[50:53], v[152:155], v[194:197], v[50:53]
	v_mfma_f32_16x16x32_bf16 v[42:45], v[160:163], v[194:197], v[42:45]
	v_mfma_f32_16x16x32_bf16 v[34:37], v[152:155], v[202:205], v[34:37]
	v_mfma_f32_16x16x32_bf16 v[26:29], v[160:163], v[202:205], v[26:29]
	v_mfma_f32_16x16x32_bf16 v[62:65], v[156:159], v[190:193], v[62:65]
	v_mfma_f32_16x16x32_bf16 v[58:61], v[164:167], v[190:193], v[58:61]
	v_mfma_f32_16x16x32_bf16 v[50:53], v[156:159], v[198:201], v[50:53]
	v_mfma_f32_16x16x32_bf16 v[42:45], v[164:167], v[198:201], v[42:45]
	v_mfma_f32_16x16x32_bf16 v[34:37], v[156:159], v[206:209], v[34:37]
	v_mfma_f32_16x16x32_bf16 v[26:29], v[164:167], v[206:209], v[26:29]
	v_mfma_f32_16x16x32_bf16 v[54:57], v[168:171], v[186:189], v[54:57]
	v_mfma_f32_16x16x32_bf16 v[46:49], v[178:181], v[186:189], v[46:49]
	v_mfma_f32_16x16x32_bf16 v[38:41], v[168:171], v[194:197], v[38:41]
	v_mfma_f32_16x16x32_bf16 v[30:33], v[178:181], v[194:197], v[30:33]
	v_mfma_f32_16x16x32_bf16 v[22:25], v[168:171], v[202:205], v[22:25]
	v_mfma_f32_16x16x32_bf16 v[14:17], v[178:181], v[202:205], v[14:17]
	v_mfma_f32_16x16x32_bf16 v[54:57], v[174:177], v[190:193], v[54:57]
	v_mfma_f32_16x16x32_bf16 v[46:49], v[182:185], v[190:193], v[46:49]
	v_mfma_f32_16x16x32_bf16 v[38:41], v[174:177], v[198:201], v[38:41]
	v_mfma_f32_16x16x32_bf16 v[30:33], v[182:185], v[198:201], v[30:33]
	v_mfma_f32_16x16x32_bf16 v[22:25], v[174:177], v[206:209], v[22:25]
	v_mfma_f32_16x16x32_bf16 v[14:17], v[182:185], v[206:209], v[14:17]
	s_barrier
	s_add_i32 s65, 0, 0x18000
	s_add_i32 s66, 0, 0x1c000
	v_add_u32_e32 v164, s65, v150
	v_add_u32_e32 v173, s66, v150
	ds_read_b128 v[152:155], v164
	ds_read_b128 v[156:159], v164 offset:1024
	ds_read_b128 v[160:163], v164 offset:2048
	ds_read_b128 v[164:167], v164 offset:3072
	ds_read_b128 v[168:171], v173
	ds_read_b128 v[174:177], v173 offset:1024
	ds_read_b128 v[178:181], v173 offset:2048
	ds_read_b128 v[182:185], v173 offset:3072
	s_add_u32 s30, s30, 0xc0000
	s_addc_u32 s31, s31, 0
	s_mov_b32 m0, s42
	v_lshl_add_u64 v[226:227], s[30:31], 0, v[136:137]
	ds_read_b128 v[186:189], v151 offset:32768
	ds_read_b128 v[190:193], v151 offset:33792
	ds_read_b128 v[194:197], v151 offset:34816
	ds_read_b128 v[198:201], v151 offset:35840
	ds_read_b128 v[202:205], v151 offset:36864
	ds_read_b128 v[206:209], v151 offset:37888
	global_load_lds_dwordx4 v[226:227], off
	v_lshl_add_u64 v[226:227], s[30:31], 0, v[124:125]
	s_mov_b32 m0, s43
	s_nop 0
	global_load_lds_dwordx4 v[226:227], off
	s_waitcnt vmcnt(8)
	s_waitcnt lgkmcnt(0)
	s_barrier
	s_waitcnt lgkmcnt(0)
	v_mfma_f32_16x16x32_bf16 v[114:117], v[152:155], v[186:189], v[114:117]
	v_mfma_f32_16x16x32_bf16 v[106:109], v[160:163], v[186:189], v[106:109]
	v_mfma_f32_16x16x32_bf16 v[130:133], v[152:155], v[194:197], v[130:133]
	v_mfma_f32_16x16x32_bf16 v[78:81], v[160:163], v[194:197], v[78:81]
	v_mfma_f32_16x16x32_bf16 v[126:129], v[152:155], v[202:205], v[126:129]
	v_mfma_f32_16x16x32_bf16 v[118:121], v[160:163], v[202:205], v[118:121]
	v_mfma_f32_16x16x32_bf16 v[114:117], v[156:159], v[190:193], v[114:117]
	v_mfma_f32_16x16x32_bf16 v[106:109], v[164:167], v[190:193], v[106:109]
	v_mfma_f32_16x16x32_bf16 v[130:133], v[156:159], v[198:201], v[130:133]
	v_mfma_f32_16x16x32_bf16 v[78:81], v[164:167], v[198:201], v[78:81]
	v_mfma_f32_16x16x32_bf16 v[126:129], v[156:159], v[206:209], v[126:129]
	v_mfma_f32_16x16x32_bf16 v[118:121], v[164:167], v[206:209], v[118:121]
	v_mfma_f32_16x16x32_bf16 v[98:101], v[168:171], v[186:189], v[98:101]
	v_mfma_f32_16x16x32_bf16 v[82:85], v[178:181], v[186:189], v[82:85]
	v_mfma_f32_16x16x32_bf16 v[86:89], v[168:171], v[194:197], v[86:89]
	v_mfma_f32_16x16x32_bf16 v[90:93], v[178:181], v[194:197], v[90:93]
	v_mfma_f32_16x16x32_bf16 v[110:113], v[168:171], v[202:205], v[110:113]
	v_mfma_f32_16x16x32_bf16 v[94:97], v[178:181], v[202:205], v[94:97]
	v_mfma_f32_16x16x32_bf16 v[98:101], v[174:177], v[190:193], v[98:101]
	v_mfma_f32_16x16x32_bf16 v[82:85], v[182:185], v[190:193], v[82:85]
	v_mfma_f32_16x16x32_bf16 v[86:89], v[174:177], v[198:201], v[86:89]
	v_mfma_f32_16x16x32_bf16 v[90:93], v[182:185], v[198:201], v[90:93]
	v_mfma_f32_16x16x32_bf16 v[110:113], v[174:177], v[206:209], v[110:113]
	v_mfma_f32_16x16x32_bf16 v[94:97], v[182:185], v[206:209], v[94:97]
	s_barrier
	s_add_i32 s30, s65, s35
	v_lshl_add_u64 v[218:219], v[218:219], 0, s[16:17]
	s_mov_b32 m0, s30
	ds_read_b128 v[186:189], v151 offset:49152
	ds_read_b128 v[190:193], v151 offset:50176
	ds_read_b128 v[194:197], v151 offset:51200
	ds_read_b128 v[198:201], v151 offset:52224
	ds_read_b128 v[202:205], v151 offset:53248
	ds_read_b128 v[206:209], v151 offset:54272
	global_load_lds_dwordx4 v[218:219], off
	s_add_i32 m0, s30, 0x2000
	s_add_u32 s28, s28, 0x100080
	v_lshl_add_u64 v[218:219], v[220:221], 0, s[16:17]
	s_addc_u32 s29, s29, 0
	s_add_i32 s30, s66, s35
	global_load_lds_dwordx4 v[218:219], off
	v_lshl_add_u64 v[218:219], s[28:29], 0, v[134:135]
	s_mov_b32 m0, s30
	s_nop 0
	global_load_lds_dwordx4 v[218:219], off
	v_lshl_add_u64 v[218:219], s[28:29], 0, v[122:123]
	s_add_i32 m0, s30, 0x2000
	s_nop 0
	global_load_lds_dwordx4 v[218:219], off
	v_lshl_add_u64 v[218:219], v[222:223], 0, s[16:17]
	s_mov_b32 m0, s45
	s_nop 0
	global_load_lds_dwordx4 v[218:219], off
	v_lshl_add_u64 v[218:219], v[224:225], 0, s[16:17]
	s_mov_b32 m0, s56
	s_nop 0
	global_load_lds_dwordx4 v[218:219], off
	s_waitcnt vmcnt(8)
	s_waitcnt lgkmcnt(0)
	s_barrier
	s_waitcnt lgkmcnt(0)
	v_mfma_f32_16x16x32_bf16 v[62:65], v[152:155], v[186:189], v[62:65]
	v_mfma_f32_16x16x32_bf16 v[58:61], v[160:163], v[186:189], v[58:61]
	v_mfma_f32_16x16x32_bf16 v[50:53], v[152:155], v[194:197], v[50:53]
	v_mfma_f32_16x16x32_bf16 v[42:45], v[160:163], v[194:197], v[42:45]
	v_mfma_f32_16x16x32_bf16 v[34:37], v[152:155], v[202:205], v[34:37]
	v_mfma_f32_16x16x32_bf16 v[26:29], v[160:163], v[202:205], v[26:29]
	v_mfma_f32_16x16x32_bf16 v[62:65], v[156:159], v[190:193], v[62:65]
	v_mfma_f32_16x16x32_bf16 v[58:61], v[164:167], v[190:193], v[58:61]
	v_mfma_f32_16x16x32_bf16 v[50:53], v[156:159], v[198:201], v[50:53]
	v_mfma_f32_16x16x32_bf16 v[42:45], v[164:167], v[198:201], v[42:45]
	v_mfma_f32_16x16x32_bf16 v[34:37], v[156:159], v[206:209], v[34:37]
	v_mfma_f32_16x16x32_bf16 v[26:29], v[164:167], v[206:209], v[26:29]
	v_mfma_f32_16x16x32_bf16 v[54:57], v[168:171], v[186:189], v[54:57]
	v_mfma_f32_16x16x32_bf16 v[46:49], v[178:181], v[186:189], v[46:49]
	v_mfma_f32_16x16x32_bf16 v[38:41], v[168:171], v[194:197], v[38:41]
	v_mfma_f32_16x16x32_bf16 v[30:33], v[178:181], v[194:197], v[30:33]
	v_mfma_f32_16x16x32_bf16 v[22:25], v[168:171], v[202:205], v[22:25]
	v_mfma_f32_16x16x32_bf16 v[14:17], v[178:181], v[202:205], v[14:17]
	v_mfma_f32_16x16x32_bf16 v[54:57], v[174:177], v[190:193], v[54:57]
	v_mfma_f32_16x16x32_bf16 v[46:49], v[182:185], v[190:193], v[46:49]
	v_mfma_f32_16x16x32_bf16 v[38:41], v[174:177], v[198:201], v[38:41]
	v_mfma_f32_16x16x32_bf16 v[30:33], v[182:185], v[198:201], v[30:33]
	v_mfma_f32_16x16x32_bf16 v[22:25], v[174:177], v[206:209], v[22:25]
	v_mfma_f32_16x16x32_bf16 v[14:17], v[182:185], v[206:209], v[14:17]
	s_barrier
	s_add_i32 s64, s64, 2
	s_add_u32 s26, s26, 0x100
	s_addc_u32 s27, s27, 0
	s_cmp_gt_u32 s64, 61
	s_cbranch_scc0 .LBB0_649
	s_add_u32 s26, s60, 0xffffff00
	s_addc_u32 s27, s61, -1
	s_andn2_b64 vcc, exec, s[4:5]
	s_cbranch_vccnz .LBB0_644
	v_mov_b32_e32 v2, 0
	s_mov_b32 s10, s18
	s_mov_b32 s6, s20
	s_mov_b64 s[14:15], s[24:25]
	s_mov_b32 s44, s59
	v_mov_b32_e32 v3, v2
	v_mov_b32_e32 v4, v2
	v_mov_b32_e32 v5, v2
	v_mov_b32_e32 v6, v2
	v_mov_b32_e32 v7, v2
	v_mov_b32_e32 v8, v2
	v_mov_b32_e32 v9, v2
	v_mov_b32_e32 v14, v2
	v_mov_b32_e32 v15, v2
	v_mov_b32_e32 v16, v2
	v_mov_b32_e32 v17, v2
	v_mov_b32_e32 v22, v2
	v_mov_b32_e32 v23, v2
	v_mov_b32_e32 v24, v2
	v_mov_b32_e32 v25, v2
	v_mov_b32_e32 v30, v2
	v_mov_b32_e32 v31, v2
	v_mov_b32_e32 v32, v2
	v_mov_b32_e32 v33, v2
	v_mov_b32_e32 v38, v2
	v_mov_b32_e32 v39, v2
	v_mov_b32_e32 v40, v2
	v_mov_b32_e32 v41, v2
	v_mov_b32_e32 v46, v2
	v_mov_b32_e32 v47, v2
	v_mov_b32_e32 v48, v2
	v_mov_b32_e32 v49, v2
	v_mov_b32_e32 v54, v2
	v_mov_b32_e32 v55, v2
	v_mov_b32_e32 v56, v2
	v_mov_b32_e32 v57, v2
	v_mov_b32_e32 v10, v2
	v_mov_b32_e32 v11, v2
	v_mov_b32_e32 v12, v2
	v_mov_b32_e32 v13, v2
	v_mov_b32_e32 v18, v2
	v_mov_b32_e32 v19, v2
	v_mov_b32_e32 v20, v2
	v_mov_b32_e32 v21, v2
	v_mov_b32_e32 v26, v2
	v_mov_b32_e32 v27, v2
	v_mov_b32_e32 v28, v2
	v_mov_b32_e32 v29, v2
	v_mov_b32_e32 v34, v2
	v_mov_b32_e32 v35, v2
	v_mov_b32_e32 v36, v2
	v_mov_b32_e32 v37, v2
	v_mov_b32_e32 v42, v2
	v_mov_b32_e32 v43, v2
	v_mov_b32_e32 v44, v2
	v_mov_b32_e32 v45, v2
	v_mov_b32_e32 v50, v2
	v_mov_b32_e32 v51, v2
	v_mov_b32_e32 v52, v2
	v_mov_b32_e32 v53, v2
	v_mov_b32_e32 v58, v2
	v_mov_b32_e32 v59, v2
	v_mov_b32_e32 v60, v2
	v_mov_b32_e32 v61, v2
	v_mov_b32_e32 v62, v2
	v_mov_b32_e32 v63, v2
	v_mov_b32_e32 v64, v2
	v_mov_b32_e32 v65, v2
	v_mov_b32_e32 v66, v2
	v_mov_b32_e32 v67, v2
	v_mov_b32_e32 v68, v2
	v_mov_b32_e32 v69, v2
	v_mov_b32_e32 v70, v2
	v_mov_b32_e32 v71, v2
	v_mov_b32_e32 v72, v2
	v_mov_b32_e32 v73, v2
	v_mov_b32_e32 v94, v2
	v_mov_b32_e32 v95, v2
	v_mov_b32_e32 v96, v2
	v_mov_b32_e32 v97, v2
	v_mov_b32_e32 v110, v2
	v_mov_b32_e32 v111, v2
	v_mov_b32_e32 v112, v2
	v_mov_b32_e32 v113, v2
	v_mov_b32_e32 v90, v2
	v_mov_b32_e32 v91, v2
	v_mov_b32_e32 v92, v2
	v_mov_b32_e32 v93, v2
	v_mov_b32_e32 v86, v2
	v_mov_b32_e32 v87, v2
	v_mov_b32_e32 v88, v2
	v_mov_b32_e32 v89, v2
	v_mov_b32_e32 v82, v2
	v_mov_b32_e32 v83, v2
	v_mov_b32_e32 v84, v2
	v_mov_b32_e32 v85, v2
	v_mov_b32_e32 v98, v2
	v_mov_b32_e32 v99, v2
	v_mov_b32_e32 v100, v2
	v_mov_b32_e32 v101, v2
	v_mov_b32_e32 v74, v2
	v_mov_b32_e32 v75, v2
	v_mov_b32_e32 v76, v2
	v_mov_b32_e32 v77, v2
	v_mov_b32_e32 v102, v2
	v_mov_b32_e32 v103, v2
	v_mov_b32_e32 v104, v2
	v_mov_b32_e32 v105, v2
	v_mov_b32_e32 v118, v2
	v_mov_b32_e32 v119, v2
	v_mov_b32_e32 v120, v2
	v_mov_b32_e32 v121, v2
	v_mov_b32_e32 v126, v2
	v_mov_b32_e32 v127, v2
	v_mov_b32_e32 v128, v2
	v_mov_b32_e32 v129, v2
	v_mov_b32_e32 v78, v2
	v_mov_b32_e32 v79, v2
	v_mov_b32_e32 v80, v2
	v_mov_b32_e32 v81, v2
	v_mov_b32_e32 v130, v2
	v_mov_b32_e32 v131, v2
	v_mov_b32_e32 v132, v2
	v_mov_b32_e32 v133, v2
	v_mov_b32_e32 v106, v2
	v_mov_b32_e32 v107, v2
	v_mov_b32_e32 v108, v2
	v_mov_b32_e32 v109, v2
	v_mov_b32_e32 v114, v2
	v_mov_b32_e32 v115, v2
	v_mov_b32_e32 v116, v2
	v_mov_b32_e32 v117, v2
	s_andn2_b64 vcc, exec, s[0:1]
	s_cbranch_vccnz .LBB0_645
